# scan step blocks: independent DPP reduction chains interleaved, DPP wait-state gaps filled with nearby independent FMAs, s_nop pads re-derived (213 -> 33 wait states per chunk), adjacent lgkmcnt waits
# speedup vs baseline: 1.0020x; 1.0020x over previous
.LBB0_1069:
	s_bitcmp1_b32 s52, 0
	s_cselect_b32 s10, 0x6000, 0
	s_add_i32 s10, s97, s10
	v_lshl_add_u32 v83, v75, 2, s10
	ds_read_b128 v[126:129], v83
	ds_read_b128 v[130:133], v83 offset:16
	ds_read_b128 v[134:137], v83 offset:512
	ds_read_b128 v[62:65], v83 offset:528
	ds_read_b128 v[58:61], v83 offset:256
	ds_read_b128 v[54:57], v83 offset:272
	s_lshl_b32 s11, s4, 2
	s_add_i32 s10, s10, s11
	v_lshl_add_u32 v82, v72, 2, s10
	s_waitcnt lgkmcnt(5)
	v_mul_f32_e32 v67, v46, v126
	v_mul_f32_e32 v68, v38, v126
	v_fmac_f32_e32 v67, v47, v127
	v_fmac_f32_e32 v68, v39, v127
	v_fmac_f32_e32 v67, v48, v128
	v_fmac_f32_e32 v68, v40, v128
	v_fmac_f32_e32 v67, v49, v129
	v_fmac_f32_e32 v68, v41, v129
	s_waitcnt lgkmcnt(4)
	v_fmac_f32_e32 v67, v42, v130
	v_fmac_f32_e32 v68, v34, v130
	v_fmac_f32_e32 v67, v43, v131
	v_fmac_f32_e32 v68, v35, v131
	v_fmac_f32_e32 v67, v44, v132
	v_fmac_f32_e32 v68, v36, v132
	v_fmac_f32_e32 v67, v45, v133
	v_fmac_f32_e32 v68, v37, v133
	v_add_u32_e32 v66, 0x100, v82
	ds_read2st64_b64 v[50:53], v66 offset0:2 offset1:5
	ds_read_b128 v[138:141], v83 offset:768
	ds_read_b128 v[142:145], v83 offset:784
	ds_read_b128 v[126:129], v83 offset:1536
	ds_read_b128 v[130:133], v83 offset:1552
	v_add_f32_dpp v67, v67, v67 quad_perm:[1,0,3,2] row_mask:0xf bank_mask:0xf bound_ctrl:1
	v_add_f32_dpp v68, v68, v68 quad_perm:[1,0,3,2] row_mask:0xf bank_mask:0xf bound_ctrl:1
	s_nop 0
	v_add_f32_dpp v67, v67, v67 quad_perm:[2,3,0,1] row_mask:0xf bank_mask:0xf bound_ctrl:1
	v_add_f32_dpp v68, v68, v68 quad_perm:[2,3,0,1] row_mask:0xf bank_mask:0xf bound_ctrl:1
	ds_read_b128 v[146:149], v83 offset:1024
	ds_read_b128 v[150:153], v83 offset:1040
	v_add_f32_dpp v67, v67, v67 row_half_mirror row_mask:0xf bank_mask:0xf bound_ctrl:1
	v_add_f32_dpp v68, v68, v68 row_half_mirror row_mask:0xf bank_mask:0xf bound_ctrl:1
	ds_read_b128 v[154:157], v83 offset:2048
	ds_read_b128 v[158:161], v83 offset:2064
	s_waitcnt lgkmcnt(11)
	v_mul_f32_e32 v69, v134, v67
	v_mul_f32_e32 v70, v135, v67
	v_mul_f32_e32 v80, v136, v67
	v_mul_f32_e32 v81, v137, v67
	v_mul_f32_e32 v98, v62, v67
	v_mul_f32_e32 v99, v63, v67
	ds_read_b128 v[162:165], v83 offset:1792
	v_mul_f32_e32 v103, v64, v67
	ds_read_b128 v[178:181], v83 offset:1808
	v_mul_f32_e32 v67, v65, v67
	s_waitcnt lgkmcnt(11)
	v_fmac_f32_e32 v69, v46, v58
	v_fmac_f32_e32 v70, v47, v59
	v_fmac_f32_e32 v80, v48, v60
	v_fmac_f32_e32 v81, v49, v61
	v_fmac_f32_e32 v98, v42, v54
	v_fmac_f32_e32 v99, v43, v55
	v_fmac_f32_e32 v103, v44, v56
	v_fmac_f32_e32 v67, v45, v57
	s_waitcnt lgkmcnt(9)
	v_fmac_f32_e32 v69, v50, v138
	v_fmac_f32_e32 v70, v50, v139
	v_fmac_f32_e32 v80, v50, v140
	v_fmac_f32_e32 v81, v50, v141
	s_waitcnt lgkmcnt(8)
	v_fmac_f32_e32 v98, v50, v142
	v_fmac_f32_e32 v99, v50, v143
	v_fmac_f32_e32 v103, v50, v144
	v_fmac_f32_e32 v67, v50, v145
	v_mul_f32_e32 v50, v134, v68
	v_fmac_f32_e32 v50, v38, v58
	v_mul_f32_e32 v121, v135, v68
	v_fmac_f32_e32 v50, v51, v138
	v_mul_f32_e32 v125, v136, v68
	v_mul_f32_e32 v138, v137, v68
	v_fmac_f32_e32 v121, v39, v59
	v_fmac_f32_e32 v125, v40, v60
	v_fmac_f32_e32 v138, v41, v61
	v_fmac_f32_e32 v121, v51, v139
	v_fmac_f32_e32 v125, v51, v140
	v_fmac_f32_e32 v138, v51, v141
	v_mul_f32_e32 v139, v62, v68
	v_mul_f32_e32 v140, v63, v68
	v_mul_f32_e32 v141, v64, v68
	v_mul_f32_e32 v68, v65, v68
	v_fmac_f32_e32 v139, v34, v54
	v_fmac_f32_e32 v140, v35, v55
	v_fmac_f32_e32 v141, v36, v56
	v_fmac_f32_e32 v68, v37, v57
	v_fmac_f32_e32 v139, v51, v142
	v_fmac_f32_e32 v140, v51, v143
	v_fmac_f32_e32 v141, v51, v144
	v_fmac_f32_e32 v68, v51, v145
	s_waitcnt lgkmcnt(5)
	v_mul_f32_e32 v51, v69, v126
	v_mul_f32_e32 v126, v50, v126
	v_fmac_f32_e32 v51, v70, v127
	v_fmac_f32_e32 v126, v121, v127
	v_fmac_f32_e32 v51, v80, v128
	ds_read_b128 v[62:65], v83 offset:2304
	ds_read_b128 v[34:37], v83 offset:2320
	v_fmac_f32_e32 v126, v125, v128
	v_fmac_f32_e32 v51, v81, v129
	v_fmac_f32_e32 v126, v138, v129
	ds_read_b128 v[46:49], v83 offset:3072
	v_fmac_f32_e32 v51, v98, v130
	v_fmac_f32_e32 v126, v139, v130
	v_fmac_f32_e32 v51, v99, v131
	v_fmac_f32_e32 v126, v140, v131
	v_fmac_f32_e32 v51, v103, v132
	v_fmac_f32_e32 v126, v141, v132
	v_mul_f32_e32 v95, v146, v69
	v_fmac_f32_e32 v51, v67, v133
	v_fmac_f32_e32 v126, v68, v133
	v_mul_f32_e32 v96, v146, v50
	v_add_f32_dpp v51, v51, v51 quad_perm:[1,0,3,2] row_mask:0xf bank_mask:0xf bound_ctrl:1
	v_add_f32_dpp v126, v126, v126 quad_perm:[1,0,3,2] row_mask:0xf bank_mask:0xf bound_ctrl:1
	ds_read_b128 v[38:41], v83 offset:3088
	v_add_f32_dpp v51, v51, v51 quad_perm:[2,3,0,1] row_mask:0xf bank_mask:0xf bound_ctrl:1
	v_add_f32_dpp v126, v126, v126 quad_perm:[2,3,0,1] row_mask:0xf bank_mask:0xf bound_ctrl:1
	v_fmac_f32_e32 v95, v70, v147
	v_add_f32_dpp v51, v51, v51 row_half_mirror row_mask:0xf bank_mask:0xf bound_ctrl:1
	v_add_f32_dpp v126, v126, v126 row_half_mirror row_mask:0xf bank_mask:0xf bound_ctrl:1
	v_fmac_f32_e32 v96, v121, v147
	s_waitcnt lgkmcnt(4)
	v_mul_f32_e32 v145, v155, v126
	v_fmac_f32_e32 v95, v80, v148
	v_fmac_f32_e32 v96, v125, v148
	v_fmac_f32_e32 v145, v121, v163
	v_mul_f32_e32 v121, v156, v126
	v_fmac_f32_e32 v95, v81, v149
	v_fmac_f32_e32 v96, v138, v149
	v_mul_f32_e32 v142, v154, v51
	v_fmac_f32_e32 v121, v125, v164
	v_mul_f32_e32 v125, v157, v126
	ds_read_b128 v[54:57], v83 offset:3584
	ds_read_b128 v[58:61], v83 offset:3600
	v_fmac_f32_e32 v95, v98, v150
	v_fmac_f32_e32 v96, v139, v150
	v_fmac_f32_e32 v142, v69, v162
	v_mul_f32_e32 v69, v155, v51
	ds_read_b128 v[130:133], v83 offset:2560
	ds_read_b128 v[134:137], v83 offset:2576
	ds_read_b128 v[42:45], v83 offset:3328
	v_fmac_f32_e32 v125, v138, v165
	ds_read_b128 v[188:191], v83 offset:3344
	v_mul_f32_e32 v138, v158, v126
	v_fmac_f32_e32 v95, v99, v151
	v_fmac_f32_e32 v69, v70, v163
	v_mul_f32_e32 v70, v156, v51
	v_mul_f32_e32 v144, v160, v51
	v_fmac_f32_e32 v138, v139, v178
	v_mul_f32_e32 v139, v159, v126
	v_fmac_f32_e32 v96, v140, v151
	v_fmac_f32_e32 v95, v103, v152
	v_fmac_f32_e32 v70, v80, v164
	v_mul_f32_e32 v80, v157, v51
	v_fmac_f32_e32 v144, v103, v180
	v_mul_f32_e32 v103, v161, v51
	v_fmac_f32_e32 v139, v140, v179
	v_mul_f32_e32 v140, v160, v126
	v_fmac_f32_e32 v96, v141, v152
	v_fmac_f32_e32 v95, v67, v153
	v_fmac_f32_e32 v80, v81, v165
	v_mul_f32_e32 v81, v158, v51
	v_mul_f32_e32 v143, v159, v51
	v_fmac_f32_e32 v103, v67, v181
	v_mul_f32_e32 v67, v154, v126
	v_fmac_f32_e32 v140, v141, v180
	v_mul_f32_e32 v141, v161, v126
	v_fmac_f32_e32 v81, v98, v178
	v_fmac_f32_e32 v143, v99, v179
	v_fmac_f32_e32 v67, v50, v162
	v_fmac_f32_e32 v141, v68, v181
	s_waitcnt lgkmcnt(7)
	v_fmac_f32_e32 v142, v52, v62
	v_fmac_f32_e32 v69, v52, v63
	v_fmac_f32_e32 v70, v52, v64
	ds_read2st64_b64 v[154:157], v66 offset0:8 offset1:11
	v_fmac_f32_e32 v80, v52, v65
	v_fmac_f32_e32 v81, v52, v34
	v_fmac_f32_e32 v143, v52, v35
	v_fmac_f32_e32 v144, v52, v36
	ds_read_b128 v[148:151], v83 offset:3840
	ds_read_b128 v[126:129], v83 offset:3856
	v_fmac_f32_e32 v103, v52, v37
	v_fmac_f32_e32 v67, v53, v62
	v_fmac_f32_e32 v145, v53, v63
	v_fmac_f32_e32 v121, v53, v64
	v_fmac_f32_e32 v125, v53, v65
	v_fmac_f32_e32 v138, v53, v34
	v_fmac_f32_e32 v139, v53, v35
	v_fmac_f32_e32 v140, v53, v36
	v_fmac_f32_e32 v141, v53, v37
	v_fmac_f32_e32 v96, v68, v153
	v_mul_f32_e32 v68, v142, v46
	v_mul_f32_e32 v46, v67, v46
	v_fmac_f32_e32 v68, v69, v47
	v_fmac_f32_e32 v46, v145, v47
	v_fmac_f32_e32 v68, v70, v48
	v_fmac_f32_e32 v46, v121, v48
	v_fmac_f32_e32 v68, v80, v49
	v_fmac_f32_e32 v46, v125, v49
	s_waitcnt lgkmcnt(4)
	v_fmac_f32_e32 v68, v81, v38
	v_fmac_f32_e32 v46, v138, v38
	v_fmac_f32_e32 v68, v143, v39
	v_fmac_f32_e32 v46, v139, v39
	v_fmac_f32_e32 v68, v144, v40
	v_fmac_f32_e32 v46, v140, v40
	v_fmac_f32_e32 v68, v103, v41
	v_fmac_f32_e32 v46, v141, v41
	ds_read_b128 v[34:37], v83 offset:4608
	ds_read_b128 v[38:41], v83 offset:4624
	v_add_f32_dpp v68, v68, v68 quad_perm:[1,0,3,2] row_mask:0xf bank_mask:0xf bound_ctrl:1
	v_add_f32_dpp v46, v46, v46 quad_perm:[1,0,3,2] row_mask:0xf bank_mask:0xf bound_ctrl:1
	s_nop 0
	v_add_f32_dpp v68, v68, v68 quad_perm:[2,3,0,1] row_mask:0xf bank_mask:0xf bound_ctrl:1
	v_add_f32_dpp v46, v46, v46 quad_perm:[2,3,0,1] row_mask:0xf bank_mask:0xf bound_ctrl:1
	s_nop 0
	v_add_f32_dpp v68, v68, v68 row_half_mirror row_mask:0xf bank_mask:0xf bound_ctrl:1
	v_add_f32_dpp v46, v46, v46 row_half_mirror row_mask:0xf bank_mask:0xf bound_ctrl:1
	v_mul_f32_e32 v146, v54, v68
	v_mul_f32_e32 v98, v130, v142
	v_fmac_f32_e32 v146, v142, v42
	v_mul_f32_e32 v142, v55, v68
	v_fmac_f32_e32 v98, v69, v131
	v_fmac_f32_e32 v142, v69, v43
	v_mul_f32_e32 v69, v56, v68
	v_fmac_f32_e32 v98, v70, v132
	v_fmac_f32_e32 v69, v70, v44
	v_mul_f32_e32 v70, v57, v68
	v_fmac_f32_e32 v98, v80, v133
	v_fmac_f32_e32 v70, v80, v45
	v_mul_f32_e32 v80, v58, v68
	v_mul_f32_e32 v99, v130, v67
	ds_read_b128 v[62:65], v83 offset:5120
	ds_read_b128 v[158:161], v83 offset:5136
	v_fmac_f32_e32 v98, v81, v134
	ds_read_b128 v[162:165], v83 offset:4096
	v_fmac_f32_e32 v99, v145, v131
	ds_read_b128 v[50:53], v83 offset:4864
	s_waitcnt lgkmcnt(6)
	v_fmac_f32_e32 v80, v81, v188
	ds_read_b128 v[178:181], v83 offset:4880
	v_mul_f32_e32 v81, v59, v68
	v_fmac_f32_e32 v98, v143, v135
	v_fmac_f32_e32 v81, v143, v189
	v_mul_f32_e32 v143, v60, v68
	v_mul_f32_e32 v68, v61, v68
	v_fmac_f32_e32 v99, v121, v132
	v_fmac_f32_e32 v143, v144, v190
	v_fmac_f32_e32 v68, v103, v191
	v_fmac_f32_e32 v99, v125, v133
	v_fmac_f32_e32 v146, v154, v148
	ds_read_b128 v[194:197], v83 offset:4112
	v_fmac_f32_e32 v142, v154, v149
	v_fmac_f32_e32 v69, v154, v150
	v_fmac_f32_e32 v70, v154, v151
	v_fmac_f32_e32 v80, v154, v126
	v_fmac_f32_e32 v81, v154, v127
	v_fmac_f32_e32 v143, v154, v128
	v_fmac_f32_e32 v68, v154, v129
	v_mul_f32_e32 v154, v54, v46
	v_mul_f32_e32 v147, v58, v46
	v_fmac_f32_e32 v99, v138, v134
	v_fmac_f32_e32 v154, v67, v42
	v_mul_f32_e32 v67, v55, v46
	v_fmac_f32_e32 v147, v138, v188
	v_mul_f32_e32 v138, v59, v46
	v_fmac_f32_e32 v99, v139, v135
	v_fmac_f32_e32 v98, v144, v136
	v_fmac_f32_e32 v67, v145, v43
	v_mul_f32_e32 v144, v56, v46
	v_mul_f32_e32 v145, v57, v46
	v_fmac_f32_e32 v138, v139, v189
	v_mul_f32_e32 v139, v60, v46
	v_fmac_f32_e32 v99, v140, v136
	v_fmac_f32_e32 v144, v121, v44
	v_fmac_f32_e32 v145, v125, v45
	v_fmac_f32_e32 v139, v140, v190
	v_mul_f32_e32 v140, v61, v46
	v_fmac_f32_e32 v140, v141, v191
	v_fmac_f32_e32 v154, v155, v148
	v_fmac_f32_e32 v67, v155, v149
	v_fmac_f32_e32 v144, v155, v150
	v_fmac_f32_e32 v145, v155, v151
	v_fmac_f32_e32 v147, v155, v126
	v_fmac_f32_e32 v138, v155, v127
	v_fmac_f32_e32 v139, v155, v128
	v_fmac_f32_e32 v140, v155, v129
	s_waitcnt lgkmcnt(6)
	v_mul_f32_e32 v155, v146, v34
	v_mul_f32_e32 v34, v154, v34
	v_fmac_f32_e32 v155, v142, v35
	ds_read_b128 v[42:45], v83 offset:5376
	ds_read_b128 v[126:129], v83 offset:5392
	v_fmac_f32_e32 v34, v67, v35
	v_fmac_f32_e32 v155, v69, v36
	v_fmac_f32_e32 v34, v144, v36
	ds_read_b128 v[46:49], v83 offset:6144
	ds_read_b128 v[188:191], v83 offset:6160
	v_fmac_f32_e32 v155, v70, v37
	v_fmac_f32_e32 v34, v145, v37
	v_fmac_f32_e32 v155, v80, v38
	v_fmac_f32_e32 v34, v147, v38
	v_fmac_f32_e32 v155, v81, v39
	v_fmac_f32_e32 v34, v138, v39
	v_fmac_f32_e32 v155, v143, v40
	v_fmac_f32_e32 v34, v139, v40
	v_fmac_f32_e32 v155, v68, v41
	v_fmac_f32_e32 v34, v140, v41
	s_nop 0
	v_add_f32_dpp v155, v155, v155 quad_perm:[1,0,3,2] row_mask:0xf bank_mask:0xf bound_ctrl:1
	v_add_f32_dpp v34, v34, v34 quad_perm:[1,0,3,2] row_mask:0xf bank_mask:0xf bound_ctrl:1
	s_nop 0
	v_add_f32_dpp v155, v155, v155 quad_perm:[2,3,0,1] row_mask:0xf bank_mask:0xf bound_ctrl:1
	v_add_f32_dpp v34, v34, v34 quad_perm:[2,3,0,1] row_mask:0xf bank_mask:0xf bound_ctrl:1
	v_fmac_f32_e32 v99, v141, v137
	v_add_f32_dpp v155, v155, v155 row_half_mirror row_mask:0xf bank_mask:0xf bound_ctrl:1
	v_add_f32_dpp v34, v34, v34 row_half_mirror row_mask:0xf bank_mask:0xf bound_ctrl:1
	v_fmac_f32_e32 v98, v103, v137
	s_waitcnt lgkmcnt(4)
	v_mul_f32_e32 v141, v62, v155
	v_mul_f32_e32 v103, v162, v146
	v_fmac_f32_e32 v141, v146, v50
	v_mul_f32_e32 v146, v63, v155
	v_fmac_f32_e32 v103, v142, v163
	v_fmac_f32_e32 v146, v142, v51
	v_mul_f32_e32 v142, v64, v155
	v_fmac_f32_e32 v103, v69, v164
	v_fmac_f32_e32 v142, v69, v52
	v_mul_f32_e32 v69, v65, v155
	v_fmac_f32_e32 v103, v70, v165
	v_fmac_f32_e32 v69, v70, v53
	v_mul_f32_e32 v70, v158, v155
	ds_read_b128 v[130:133], v83 offset:5632
	ds_read_b128 v[54:57], v83 offset:6656
	ds_read_b128 v[58:61], v83 offset:6672
	v_mul_f32_e32 v121, v162, v154
	v_fmac_f32_e32 v103, v80, v194
	ds_read_b128 v[134:137], v83 offset:5648
	v_mul_f32_e32 v148, v63, v34
	ds_read_b128 v[202:205], v83 offset:6400
	ds_read_b128 v[38:41], v83 offset:6416
	v_fmac_f32_e32 v70, v80, v178
	v_mul_f32_e32 v80, v159, v155
	v_fmac_f32_e32 v121, v67, v163
	v_fmac_f32_e32 v103, v81, v195
	v_fmac_f32_e32 v148, v67, v51
	v_fmac_f32_e32 v80, v81, v179
	v_mul_f32_e32 v81, v160, v155
	v_mul_f32_e32 v67, v64, v34
	v_fmac_f32_e32 v121, v144, v164
	v_fmac_f32_e32 v103, v143, v196
	v_fmac_f32_e32 v67, v144, v52
	v_fmac_f32_e32 v81, v143, v180
	v_mul_f32_e32 v143, v161, v155
	v_mul_f32_e32 v144, v65, v34
	v_fmac_f32_e32 v121, v145, v165
	v_fmac_f32_e32 v103, v68, v197
	v_fmac_f32_e32 v144, v145, v53
	v_fmac_f32_e32 v143, v68, v181
	v_mul_f32_e32 v68, v62, v34
	v_mul_f32_e32 v145, v158, v34
	v_fmac_f32_e32 v121, v147, v194
	v_fmac_f32_e32 v68, v154, v50
	v_fmac_f32_e32 v145, v147, v178
	v_mul_f32_e32 v147, v159, v34
	v_fmac_f32_e32 v147, v138, v179
	s_waitcnt lgkmcnt(6)
	v_fmac_f32_e32 v141, v156, v42
	v_fmac_f32_e32 v68, v157, v42
	v_fmac_f32_e32 v80, v156, v127
	v_fmac_f32_e32 v146, v156, v43
	v_fmac_f32_e32 v148, v157, v43
	v_fmac_f32_e32 v147, v157, v127
	v_mul_f32_e32 v127, v141, v46
	v_mul_f32_e32 v46, v68, v46
	ds_read2st64_b64 v[162:165], v66 offset0:14 offset1:17
	v_fmac_f32_e32 v142, v156, v44
	v_fmac_f32_e32 v67, v157, v44
	v_fmac_f32_e32 v127, v146, v47
	ds_read_b128 v[62:65], v83 offset:6912
	ds_read_b128 v[50:53], v83 offset:6928
	v_fmac_f32_e32 v46, v148, v47
	v_fmac_f32_e32 v69, v156, v45
	v_fmac_f32_e32 v144, v157, v45
	v_fmac_f32_e32 v127, v142, v48
	v_fmac_f32_e32 v46, v67, v48
	v_mul_f32_e32 v149, v160, v34
	v_fmac_f32_e32 v70, v156, v126
	v_fmac_f32_e32 v145, v157, v126
	v_fmac_f32_e32 v149, v139, v180
	v_fmac_f32_e32 v127, v69, v49
	v_fmac_f32_e32 v46, v144, v49
	v_mul_f32_e32 v150, v161, v34
	v_fmac_f32_e32 v150, v140, v181
	v_fmac_f32_e32 v127, v70, v188
	v_fmac_f32_e32 v46, v145, v188
	v_fmac_f32_e32 v81, v156, v128
	v_fmac_f32_e32 v149, v157, v128
	v_fmac_f32_e32 v121, v138, v195
	v_fmac_f32_e32 v127, v80, v189
	v_fmac_f32_e32 v46, v147, v189
	v_fmac_f32_e32 v121, v139, v196
	v_fmac_f32_e32 v143, v156, v129
	v_fmac_f32_e32 v150, v157, v129
	v_fmac_f32_e32 v127, v81, v190
	v_fmac_f32_e32 v46, v149, v190
	v_fmac_f32_e32 v127, v143, v191
	v_fmac_f32_e32 v46, v150, v191
	ds_read_b128 v[42:45], v83 offset:7680
	ds_read_b128 v[34:37], v83 offset:7696
	v_fmac_f32_e32 v121, v140, v197
	s_waitcnt lgkmcnt(5)
	v_add_f32_dpp v127, v127, v127 quad_perm:[1,0,3,2] row_mask:0xf bank_mask:0xf bound_ctrl:1
	v_add_f32_dpp v46, v46, v46 quad_perm:[1,0,3,2] row_mask:0xf bank_mask:0xf bound_ctrl:1
	s_nop 0
	v_add_f32_dpp v127, v127, v127 quad_perm:[2,3,0,1] row_mask:0xf bank_mask:0xf bound_ctrl:1
	v_add_f32_dpp v46, v46, v46 quad_perm:[2,3,0,1] row_mask:0xf bank_mask:0xf bound_ctrl:1
	v_mul_f32_e32 v125, v130, v141
	v_add_f32_dpp v127, v127, v127 row_half_mirror row_mask:0xf bank_mask:0xf bound_ctrl:1
	v_add_f32_dpp v46, v46, v46 row_half_mirror row_mask:0xf bank_mask:0xf bound_ctrl:1
	v_mul_f32_e32 v152, v55, v127
	v_fmac_f32_e32 v125, v146, v131
	v_fmac_f32_e32 v152, v146, v203
	v_mul_f32_e32 v146, v56, v127
	v_fmac_f32_e32 v125, v142, v132
	v_fmac_f32_e32 v146, v142, v204
	v_mul_f32_e32 v142, v57, v127
	v_fmac_f32_e32 v125, v69, v133
	ds_read_b128 v[154:157], v83 offset:7168
	v_fmac_f32_e32 v142, v69, v205
	v_mul_f32_e32 v69, v58, v127
	v_fmac_f32_e32 v125, v70, v134
	v_fmac_f32_e32 v69, v70, v38
	v_mul_f32_e32 v70, v59, v127
	v_mul_f32_e32 v126, v130, v68
	v_fmac_f32_e32 v125, v80, v135
	v_fmac_f32_e32 v70, v80, v39
	v_mul_f32_e32 v80, v60, v127
	v_fmac_f32_e32 v125, v81, v136
	v_fmac_f32_e32 v126, v148, v131
	v_fmac_f32_e32 v80, v81, v40
	v_mul_f32_e32 v81, v61, v127
	v_fmac_f32_e32 v125, v143, v137
	v_mul_f32_e32 v151, v54, v127
	v_fmac_f32_e32 v81, v143, v41
	v_mul_f32_e32 v143, v56, v46
	v_fmac_f32_e32 v126, v67, v132
	v_fmac_f32_e32 v151, v141, v202
	v_fmac_f32_e32 v143, v67, v204
	v_mul_f32_e32 v67, v57, v46
	v_fmac_f32_e32 v126, v144, v133
	s_waitcnt lgkmcnt(3)
	v_fmac_f32_e32 v151, v162, v62
	v_fmac_f32_e32 v152, v162, v63
	v_fmac_f32_e32 v146, v162, v64
	v_fmac_f32_e32 v142, v162, v65
	v_fmac_f32_e32 v69, v162, v50
	v_fmac_f32_e32 v70, v162, v51
	v_fmac_f32_e32 v80, v162, v52
	v_fmac_f32_e32 v81, v162, v53
	v_mul_f32_e32 v162, v54, v46
	v_fmac_f32_e32 v67, v144, v205
	v_mul_f32_e32 v144, v58, v46
	v_fmac_f32_e32 v126, v145, v134
	v_fmac_f32_e32 v162, v68, v202
	v_mul_f32_e32 v68, v55, v46
	v_fmac_f32_e32 v144, v145, v38
	v_mul_f32_e32 v145, v59, v46
	v_fmac_f32_e32 v126, v147, v135
	v_fmac_f32_e32 v68, v148, v203
	v_fmac_f32_e32 v145, v147, v39
	v_mul_f32_e32 v147, v60, v46
	v_mul_f32_e32 v148, v61, v46
	v_fmac_f32_e32 v147, v149, v40
	v_fmac_f32_e32 v162, v163, v62
	v_fmac_f32_e32 v148, v150, v41
	v_fmac_f32_e32 v68, v163, v63
	v_fmac_f32_e32 v143, v163, v64
	v_fmac_f32_e32 v67, v163, v65
	v_fmac_f32_e32 v144, v163, v50
	v_fmac_f32_e32 v145, v163, v51
	v_fmac_f32_e32 v147, v163, v52
	v_fmac_f32_e32 v148, v163, v53
	s_waitcnt lgkmcnt(0)
	v_mul_f32_e32 v163, v151, v42
	v_mul_f32_e32 v42, v162, v42
	v_fmac_f32_e32 v163, v152, v43
	v_fmac_f32_e32 v42, v68, v43
	v_fmac_f32_e32 v163, v146, v44
	v_fmac_f32_e32 v42, v143, v44
	v_fmac_f32_e32 v126, v149, v136
	v_fmac_f32_e32 v163, v142, v45
	v_fmac_f32_e32 v42, v67, v45
	v_fmac_f32_e32 v163, v69, v34
	v_fmac_f32_e32 v42, v144, v34
	v_fmac_f32_e32 v126, v150, v137
	ds_read_b128 v[136:139], v83 offset:7184
	ds_read_b128 v[54:57], v83 offset:8192
	ds_read_b128 v[58:61], v83 offset:8208
	ds_read_b128 v[50:53], v83 offset:7936
	ds_read_b128 v[38:41], v83 offset:7952
	ds_read_b128 v[62:65], v83 offset:8448
	ds_read_b128 v[130:133], v83 offset:8464
	ds_read_b128 v[46:49], v83 offset:9216
	v_fmac_f32_e32 v163, v70, v35
	v_fmac_f32_e32 v42, v145, v35
	ds_read_b128 v[158:161], v83 offset:9232
	v_mul_f32_e32 v127, v154, v151
	v_fmac_f32_e32 v163, v80, v36
	v_fmac_f32_e32 v42, v147, v36
	v_fmac_f32_e32 v127, v152, v155
	v_fmac_f32_e32 v163, v81, v37
	v_fmac_f32_e32 v42, v148, v37
	v_mul_f32_e32 v128, v154, v162
	v_add_f32_dpp v163, v163, v163 quad_perm:[1,0,3,2] row_mask:0xf bank_mask:0xf bound_ctrl:1
	v_add_f32_dpp v42, v42, v42 quad_perm:[1,0,3,2] row_mask:0xf bank_mask:0xf bound_ctrl:1
	ds_read2st64_b64 v[34:37], v66 offset0:20 offset1:23
	v_add_f32_dpp v163, v163, v163 quad_perm:[2,3,0,1] row_mask:0xf bank_mask:0xf bound_ctrl:1
	ds_read_b128 v[178:181], v83 offset:8704
	v_add_f32_dpp v42, v42, v42 quad_perm:[2,3,0,1] row_mask:0xf bank_mask:0xf bound_ctrl:1
	v_add_f32_dpp v163, v163, v163 row_half_mirror row_mask:0xf bank_mask:0xf bound_ctrl:1
	v_fmac_f32_e32 v127, v146, v156
	v_add_f32_dpp v42, v42, v42 row_half_mirror row_mask:0xf bank_mask:0xf bound_ctrl:1
	v_fmac_f32_e32 v128, v68, v155
	s_waitcnt lgkmcnt(9)
	v_mul_f32_e32 v150, v55, v163
	v_fmac_f32_e32 v127, v142, v157
	ds_read_b128 v[188:191], v83 offset:8720
	v_fmac_f32_e32 v128, v143, v156
	s_waitcnt lgkmcnt(8)
	v_fmac_f32_e32 v150, v152, v51
	v_mul_f32_e32 v152, v58, v163
	v_fmac_f32_e32 v127, v69, v136
	v_fmac_f32_e32 v128, v67, v157
	s_waitcnt lgkmcnt(7)
	v_fmac_f32_e32 v152, v69, v38
	v_mul_f32_e32 v69, v59, v163
	v_mul_f32_e32 v154, v57, v42
	v_fmac_f32_e32 v127, v70, v137
	v_fmac_f32_e32 v128, v144, v136
	v_fmac_f32_e32 v69, v70, v39
	ds_read_b128 v[194:197], v83 offset:9728
	ds_read_b128 v[202:205], v83 offset:9744
	v_mul_f32_e32 v70, v60, v163
	v_fmac_f32_e32 v154, v67, v53
	v_mul_f32_e32 v67, v58, v42
	v_fmac_f32_e32 v127, v80, v138
	v_fmac_f32_e32 v67, v144, v38
	ds_read_b128 v[206:209], v83 offset:9472
	ds_read_b128 v[212:215], v83 offset:9488
	v_mul_f32_e32 v149, v54, v163
	v_fmac_f32_e32 v70, v80, v40
	v_mul_f32_e32 v80, v61, v163
	v_mul_f32_e32 v144, v59, v42
	v_fmac_f32_e32 v128, v145, v137
	v_fmac_f32_e32 v127, v81, v139
	v_mul_f32_e32 v153, v55, v42
	v_fmac_f32_e32 v149, v151, v50
	v_mul_f32_e32 v151, v56, v163
	v_fmac_f32_e32 v80, v81, v41
	v_mul_f32_e32 v81, v54, v42
	v_fmac_f32_e32 v144, v145, v39
	v_mul_f32_e32 v145, v60, v42
	v_fmac_f32_e32 v128, v147, v138
	v_fmac_f32_e32 v151, v146, v52
	v_mul_f32_e32 v146, v57, v163
	v_fmac_f32_e32 v81, v162, v50
	v_fmac_f32_e32 v153, v68, v51
	v_mul_f32_e32 v68, v56, v42
	v_fmac_f32_e32 v145, v147, v40
	v_mul_f32_e32 v147, v61, v42
	v_fmac_f32_e32 v146, v142, v53
	s_waitcnt lgkmcnt(8)
	v_fmac_f32_e32 v149, v164, v62
	v_fmac_f32_e32 v81, v165, v62
	v_fmac_f32_e32 v68, v143, v52
	v_fmac_f32_e32 v147, v148, v41
	ds_read_b128 v[38:41], v83 offset:9984
	ds_read_b128 v[54:57], v83 offset:10000
	v_fmac_f32_e32 v150, v164, v63
	v_fmac_f32_e32 v151, v164, v64
	v_fmac_f32_e32 v146, v164, v65
	v_fmac_f32_e32 v152, v164, v130
	v_fmac_f32_e32 v69, v164, v131
	v_fmac_f32_e32 v70, v164, v132
	v_fmac_f32_e32 v80, v164, v133
	v_fmac_f32_e32 v153, v165, v63
	v_fmac_f32_e32 v68, v165, v64
	v_fmac_f32_e32 v154, v165, v65
	v_fmac_f32_e32 v67, v165, v130
	v_fmac_f32_e32 v144, v165, v131
	v_fmac_f32_e32 v145, v165, v132
	v_fmac_f32_e32 v147, v165, v133
	v_mul_f32_e32 v66, v149, v46
	v_mul_f32_e32 v46, v81, v46
	v_fmac_f32_e32 v66, v150, v47
	v_fmac_f32_e32 v46, v153, v47
	v_fmac_f32_e32 v66, v151, v48
	v_fmac_f32_e32 v46, v68, v48
	v_fmac_f32_e32 v128, v148, v139
	v_fmac_f32_e32 v66, v146, v49
	v_fmac_f32_e32 v46, v154, v49
	s_waitcnt lgkmcnt(3)
	v_mul_f32_e32 v129, v178, v149
	v_fmac_f32_e32 v66, v152, v158
	v_fmac_f32_e32 v46, v67, v158
	v_fmac_f32_e32 v129, v150, v179
	v_fmac_f32_e32 v66, v69, v159
	v_fmac_f32_e32 v46, v144, v159
	v_fmac_f32_e32 v129, v151, v180
	v_fmac_f32_e32 v66, v70, v160
	v_fmac_f32_e32 v46, v145, v160
	v_fmac_f32_e32 v129, v146, v181
	ds_read_b128 v[42:45], v83 offset:10752
	ds_read_b128 v[132:135], v83 offset:10768
	v_fmac_f32_e32 v66, v80, v161
	v_fmac_f32_e32 v46, v147, v161
	v_mul_f32_e32 v130, v178, v81
	v_add_f32_dpp v66, v66, v66 quad_perm:[1,0,3,2] row_mask:0xf bank_mask:0xf bound_ctrl:1
	v_add_f32_dpp v46, v46, v46 quad_perm:[1,0,3,2] row_mask:0xf bank_mask:0xf bound_ctrl:1
	s_nop 0
	v_add_f32_dpp v66, v66, v66 quad_perm:[2,3,0,1] row_mask:0xf bank_mask:0xf bound_ctrl:1
	v_add_f32_dpp v46, v46, v46 quad_perm:[2,3,0,1] row_mask:0xf bank_mask:0xf bound_ctrl:1
	v_fmac_f32_e32 v129, v152, v188
	v_add_f32_dpp v66, v66, v66 row_half_mirror row_mask:0xf bank_mask:0xf bound_ctrl:1
	v_add_f32_dpp v46, v46, v46 row_half_mirror row_mask:0xf bank_mask:0xf bound_ctrl:1
	v_fmac_f32_e32 v130, v153, v179
	v_mul_f32_e32 v50, v194, v66
	v_fmac_f32_e32 v129, v69, v189
	v_fmac_f32_e32 v130, v68, v180
	v_fmac_f32_e32 v50, v149, v206
	v_mul_f32_e32 v53, v197, v66
	v_mul_f32_e32 v149, v204, v66
	v_fmac_f32_e32 v129, v70, v190
	ds_read_b128 v[136:139], v83 offset:10240
	ds_read_b128 v[140:143], v83 offset:10256
	v_fmac_f32_e32 v53, v146, v209
	ds_read_b128 v[58:61], v83 offset:11264
	ds_read_b128 v[62:65], v83 offset:11280
	v_mul_f32_e32 v51, v195, v66
	v_mul_f32_e32 v52, v196, v66
	v_mul_f32_e32 v146, v202, v66
	v_mul_f32_e32 v148, v203, v66
	s_waitcnt lgkmcnt(6)
	v_fmac_f32_e32 v149, v70, v214
	v_mul_f32_e32 v70, v205, v66
	v_fmac_f32_e32 v130, v154, v181
	v_fmac_f32_e32 v51, v150, v207
	v_fmac_f32_e32 v52, v151, v208
	v_fmac_f32_e32 v146, v152, v212
	v_fmac_f32_e32 v148, v69, v213
	v_fmac_f32_e32 v70, v80, v215
	v_fmac_f32_e32 v130, v67, v188
	v_fmac_f32_e32 v129, v80, v191
	v_fmac_f32_e32 v50, v34, v38
	v_fmac_f32_e32 v51, v34, v39
	v_fmac_f32_e32 v52, v34, v40
	v_fmac_f32_e32 v53, v34, v41
	v_fmac_f32_e32 v146, v34, v54
	v_fmac_f32_e32 v148, v34, v55
	v_fmac_f32_e32 v149, v34, v56
	v_fmac_f32_e32 v70, v34, v57
	v_mul_f32_e32 v34, v194, v46
	v_mul_f32_e32 v80, v195, v46
	v_mul_f32_e32 v150, v197, v46
	v_fmac_f32_e32 v130, v144, v189
	v_fmac_f32_e32 v34, v81, v206
	v_fmac_f32_e32 v80, v153, v207
	v_mul_f32_e32 v81, v196, v46
	v_fmac_f32_e32 v150, v154, v209
	v_mul_f32_e32 v151, v202, v46
	v_mul_f32_e32 v152, v203, v46
	v_mul_f32_e32 v153, v204, v46
	v_mul_f32_e32 v154, v205, v46
	v_fmac_f32_e32 v130, v145, v190
	v_fmac_f32_e32 v81, v68, v208
	v_fmac_f32_e32 v34, v35, v38
	v_fmac_f32_e32 v151, v67, v212
	v_fmac_f32_e32 v152, v144, v213
	v_fmac_f32_e32 v153, v145, v214
	v_fmac_f32_e32 v154, v147, v215
	v_fmac_f32_e32 v130, v147, v191
	v_fmac_f32_e32 v80, v35, v39
	v_fmac_f32_e32 v81, v35, v40
	v_fmac_f32_e32 v150, v35, v41
	v_fmac_f32_e32 v151, v35, v54
	v_fmac_f32_e32 v152, v35, v55
	v_fmac_f32_e32 v153, v35, v56
	v_fmac_f32_e32 v154, v35, v57
	ds_read_b128 v[54:57], v83 offset:11008
	ds_read_b128 v[38:41], v83 offset:11024
	ds_read_b128 v[66:69], v83 offset:11520
	ds_read_b128 v[156:159], v83 offset:11536
	s_waitcnt lgkmcnt(5)
	v_mul_f32_e32 v35, v50, v42
	v_mul_f32_e32 v147, v34, v42
	v_fmac_f32_e32 v35, v51, v43
	v_fmac_f32_e32 v147, v80, v43
	v_fmac_f32_e32 v35, v52, v44
	v_fmac_f32_e32 v147, v81, v44
	v_fmac_f32_e32 v35, v53, v45
	v_fmac_f32_e32 v147, v150, v45
	v_fmac_f32_e32 v35, v146, v132
	v_fmac_f32_e32 v147, v151, v132
	v_fmac_f32_e32 v35, v148, v133
	v_fmac_f32_e32 v147, v152, v133
	v_fmac_f32_e32 v35, v149, v134
	v_fmac_f32_e32 v147, v153, v134
	v_fmac_f32_e32 v35, v70, v135
	v_fmac_f32_e32 v147, v154, v135
	s_nop 0
	v_add_f32_dpp v35, v35, v35 quad_perm:[1,0,3,2] row_mask:0xf bank_mask:0xf bound_ctrl:1
	v_add_f32_dpp v147, v147, v147 quad_perm:[1,0,3,2] row_mask:0xf bank_mask:0xf bound_ctrl:1
	s_nop 0
	v_add_f32_dpp v35, v35, v35 quad_perm:[2,3,0,1] row_mask:0xf bank_mask:0xf bound_ctrl:1
	v_add_f32_dpp v147, v147, v147 quad_perm:[2,3,0,1] row_mask:0xf bank_mask:0xf bound_ctrl:1
	v_mul_f32_e32 v131, v136, v50
	v_add_f32_dpp v35, v35, v35 row_half_mirror row_mask:0xf bank_mask:0xf bound_ctrl:1
	v_add_f32_dpp v147, v147, v147 row_half_mirror row_mask:0xf bank_mask:0xf bound_ctrl:1
	v_mul_f32_e32 v132, v136, v34
	v_mul_f32_e32 v42, v58, v35
	v_mul_f32_e32 v43, v59, v35
	v_fmac_f32_e32 v131, v51, v137
	s_waitcnt lgkmcnt(3)
	v_fmac_f32_e32 v42, v50, v54
	v_fmac_f32_e32 v43, v51, v55
	v_mul_f32_e32 v44, v60, v35
	v_mul_f32_e32 v45, v61, v35
	v_mul_f32_e32 v48, v62, v35
	v_mul_f32_e32 v49, v63, v35
	v_mul_f32_e32 v50, v64, v35
	v_mul_f32_e32 v51, v65, v35
	v_fmac_f32_e32 v132, v80, v137
	v_fmac_f32_e32 v44, v52, v56
	v_fmac_f32_e32 v45, v53, v57
	s_waitcnt lgkmcnt(0)
	v_fmac_f32_e32 v48, v146, v38
	v_fmac_f32_e32 v49, v148, v39
	v_fmac_f32_e32 v50, v149, v40
	v_fmac_f32_e32 v51, v70, v41
	v_fmac_f32_e32 v42, v36, v66
	v_fmac_f32_e32 v43, v36, v67
	v_fmac_f32_e32 v44, v36, v68
	v_fmac_f32_e32 v45, v36, v69
	v_fmac_f32_e32 v48, v36, v156
	v_fmac_f32_e32 v49, v36, v157
	v_fmac_f32_e32 v50, v36, v158
	v_fmac_f32_e32 v51, v36, v159
	s_waitcnt vmcnt(7)
	v_cvt_f32_f16_e32 v36, v123
	s_add_i32 s91, s52, 1
	v_fmac_f32_e32 v131, v52, v138
	v_fmac_f32_e32 v131, v53, v139
	v_mul_f32_e32 v53, v59, v147
	v_mul_f32_e32 v59, v65, v147
	v_fmac_f32_e32 v59, v154, v41
	v_mul_f32_e32 v41, v102, v36
	v_mul_f32_e32 v46, v41, v41
	v_fmac_f32_e32 v53, v80, v55
	v_mul_f32_e32 v55, v61, v147
	v_mov_b32_dpp v46, v46 quad_perm:[1,0,3,2] row_mask:0xf bank_mask:0xf bound_ctrl:1
	v_fmac_f32_e32 v46, v41, v41
	v_fmac_f32_e32 v55, v150, v57
	v_mul_f32_e32 v57, v63, v147
	ds_read_b128 v[160:163], v83 offset:11776
	ds_read_b128 v[164:167], v83 offset:11792
	v_add_f32_dpp v46, v46, v46 quad_perm:[2,3,0,1] row_mask:0xf bank_mask:0xf bound_ctrl:1
	v_mul_f32_e32 v52, v58, v147
	v_fmac_f32_e32 v57, v152, v39
	v_mul_f32_e32 v58, v64, v147
	v_cvt_f32_f16_e32 v35, v109
	v_cvt_f32_ubyte0_e32 v39, v116
	v_add_f32_dpp v46, v46, v46 row_half_mirror row_mask:0xf bank_mask:0xf bound_ctrl:1
	v_fmac_f32_e32 v58, v153, v40
	s_bitcmp1_b32 s91, 0
	v_mul_f32_e32 v40, 0x3b808081, v39
	v_add_f32_dpp v46, v46, v46 row_mirror row_mask:0xf bank_mask:0xf bound_ctrl:1
	v_fma_f32 v39, v39, s45, -1.0
	s_cselect_b32 s10, 0x6000, 0
	v_readlane_b32 s11, v46, 16
	v_readlane_b32 s13, v46, 48
	v_fma_f32 v39, v39, v101, 1.0
	v_fmac_f32_e32 v52, v34, v54
	v_mul_f32_e32 v54, v60, v147
	v_add_u32_e32 v34, s10, v1
	v_readlane_b32 s10, v46, 0
	v_readlane_b32 s12, v46, 32
	v_mov_b32_e32 v46, s11
	v_mov_b32_e32 v47, s13
	v_mul_f32_e32 v36, v39, v36
	v_fmac_f32_e32 v54, v81, v56
	v_mul_f32_e32 v56, v62, v147
	v_add_f32_e32 v46, s10, v46
	v_add_f32_e32 v47, s12, v47
	v_mul_f32_e32 v39, v36, v35
	v_fmac_f32_e32 v56, v151, v38
	v_cvt_f32_ubyte0_e32 v38, v115
	v_add_f32_e32 v46, v46, v47
	v_mul_f32_e32 v47, v100, v39
	v_add_f32_e32 v46, 0x2b8cbccc, v46
	v_mul_f32_e32 v38, 0xbb1be179, v38
	v_mov_b32_dpp v47, v47 quad_perm:[1,0,3,2] row_mask:0xf bank_mask:0xf bound_ctrl:1
	v_fmac_f32_e32 v132, v81, v138
	v_rsq_f32_e32 v46, v46
	v_fmac_f32_e32 v47, v100, v39
	v_mul_f32_e32 v38, 0x3fb8aa3b, v38
	s_nop 0
	v_add_f32_dpp v39, v47, v47 quad_perm:[2,3,0,1] row_mask:0xf bank_mask:0xf bound_ctrl:1
	v_exp_f32_e32 v38, v38
	v_fmac_f32_e32 v132, v150, v139
	v_add_f32_dpp v39, v39, v39 row_half_mirror row_mask:0xf bank_mask:0xf bound_ctrl:1
	v_fmac_f32_e32 v131, v146, v140
	v_fmac_f32_e32 v132, v151, v140
	v_fmac_f32_e32 v131, v148, v141
	v_fmac_f32_e32 v132, v152, v141
	v_fmac_f32_e32 v52, v37, v66
	v_fmac_f32_e32 v53, v37, v67
	v_fmac_f32_e32 v54, v37, v68
	v_fmac_f32_e32 v55, v37, v69
	v_fmac_f32_e32 v56, v37, v156
	v_fmac_f32_e32 v57, v37, v157
	v_fmac_f32_e32 v58, v37, v158
	v_fmac_f32_e32 v59, v37, v159
	s_waitcnt vmcnt(6)
	v_cvt_f32_f16_e32 v37, v124
	v_add_f32_dpp v39, v39, v39 row_mirror row_mask:0xf bank_mask:0xf bound_ctrl:1
	v_fmac_f32_e32 v131, v149, v142
	v_fmac_f32_e32 v132, v153, v142
	v_readlane_b32 s14, v39, 0
	v_readlane_b32 s16, v39, 16
	v_readlane_b32 s15, v39, 32
	v_readlane_b32 s17, v39, 48
	v_add_u32_e32 v39, s48, v34
	v_mul_f32_e64 v41, v41, -v46
	v_fmac_f32_e32 v131, v70, v143
	v_fmac_f32_e32 v132, v154, v143
	ds_write2st64_b32 v39, v41, v38 offset1:1
	v_mul_f32_e64 v38, v40, -v41
	ds_write2st64_b32 v39, v38, v36 offset0:2 offset1:3
	ds_write2st64_b32 v39, v35, v37 offset0:4 offset1:5
	s_waitcnt vmcnt(5)
	v_cvt_f32_f16_e32 v36, v117
	v_cvt_f32_f16_e32 v35, v105
	v_cvt_f32_ubyte0_e32 v39, v114
	v_mul_f32_e32 v40, 0x3b808081, v39
	v_mul_f32_e32 v41, v102, v36
	v_mul_f32_e32 v46, v41, v41
	v_fma_f32 v39, v39, s45, -1.0
	v_fma_f32 v39, v39, v101, 1.0
	v_mov_b32_dpp v46, v46 quad_perm:[1,0,3,2] row_mask:0xf bank_mask:0xf bound_ctrl:1
	v_fmac_f32_e32 v46, v41, v41
	v_mul_f32_e32 v36, v39, v36
	v_mul_f32_e32 v39, v36, v35
	v_add_f32_dpp v46, v46, v46 quad_perm:[2,3,0,1] row_mask:0xf bank_mask:0xf bound_ctrl:1
	v_cvt_f32_ubyte0_e32 v38, v113
	v_mul_f32_e32 v38, 0xbb1be179, v38
	v_add_f32_dpp v46, v46, v46 row_half_mirror row_mask:0xf bank_mask:0xf bound_ctrl:1
	v_mul_f32_e32 v38, 0x3fb8aa3b, v38
	v_exp_f32_e32 v38, v38
	v_add_f32_dpp v46, v46, v46 row_mirror row_mask:0xf bank_mask:0xf bound_ctrl:1
	s_waitcnt vmcnt(4)
	v_cvt_f32_f16_e32 v37, v118
	v_readlane_b32 s11, v46, 16
	v_readlane_b32 s13, v46, 48
	v_readlane_b32 s10, v46, 0
	v_readlane_b32 s12, v46, 32
	v_mov_b32_e32 v46, s11
	v_mov_b32_e32 v47, s13
	v_add_f32_e32 v46, s10, v46
	v_add_f32_e32 v47, s12, v47
	v_add_f32_e32 v46, v46, v47
	v_mul_f32_e32 v47, v100, v39
	v_add_f32_e32 v46, 0x2b8cbccc, v46
	v_rsq_f32_e32 v46, v46
	v_mov_b32_dpp v47, v47 quad_perm:[1,0,3,2] row_mask:0xf bank_mask:0xf bound_ctrl:1
	v_fmac_f32_e32 v47, v100, v39
	v_add_u32_e32 v34, s49, v34
	s_nop 0
	v_add_f32_dpp v39, v47, v47 quad_perm:[2,3,0,1] row_mask:0xf bank_mask:0xf bound_ctrl:1
	s_waitcnt lgkmcnt(4)
	s_nop 0
	v_add_f32_dpp v39, v39, v39 row_half_mirror row_mask:0xf bank_mask:0xf bound_ctrl:1
	v_mul_f32_e32 v134, v160, v52
	v_mul_f32_e32 v133, v160, v42
	v_add_f32_dpp v39, v39, v39 row_mirror row_mask:0xf bank_mask:0xf bound_ctrl:1
	v_fmac_f32_e32 v133, v43, v161
	v_readlane_b32 s31, v39, 0
	v_readlane_b32 s53, v39, 16
	v_readlane_b32 s34, v39, 32
	v_readlane_b32 s54, v39, 48
	v_mul_f32_e64 v39, v41, -v46
	ds_write2st64_b32 v34, v39, v38 offset1:1
	v_mul_f32_e64 v38, v40, -v39
	ds_write2st64_b32 v34, v38, v36 offset0:2 offset1:3
	ds_write2st64_b32 v34, v35, v37 offset0:4 offset1:5
	v_cvt_f32_f16_e32 v36, v106
	v_cvt_f32_f16_e32 v35, v104
	s_waitcnt vmcnt(3)
	v_cvt_f32_ubyte0_e32 v39, v122
	v_mul_f32_e32 v40, 0x3b808081, v39
	v_mul_f32_e32 v41, v102, v36
	v_mul_f32_e32 v46, v41, v41
	v_fma_f32 v39, v39, s45, -1.0
	v_fma_f32 v39, v101, v39, 1.0
	v_mov_b32_dpp v46, v46 quad_perm:[1,0,3,2] row_mask:0xf bank_mask:0xf bound_ctrl:1
	v_fmac_f32_e32 v46, v41, v41
	v_mul_f32_e32 v36, v39, v36
	v_mul_f32_e32 v39, v36, v35
	v_add_f32_dpp v46, v46, v46 quad_perm:[2,3,0,1] row_mask:0xf bank_mask:0xf bound_ctrl:1
	v_cvt_f32_ubyte0_e32 v38, v112
	v_mul_f32_e32 v38, 0xbb1be179, v38
	v_add_f32_dpp v46, v46, v46 row_half_mirror row_mask:0xf bank_mask:0xf bound_ctrl:1
	v_mul_f32_e32 v38, 0x3fb8aa3b, v38
	v_exp_f32_e32 v38, v38
	v_add_f32_dpp v46, v46, v46 row_mirror row_mask:0xf bank_mask:0xf bound_ctrl:1
	v_cvt_f32_f16_e32 v37, v107
	v_readlane_b32 s11, v46, 16
	v_readlane_b32 s13, v46, 48
	v_readlane_b32 s10, v46, 0
	v_readlane_b32 s12, v46, 32
	v_mov_b32_e32 v46, s11
	v_mov_b32_e32 v47, s13
	v_add_f32_e32 v46, s10, v46
	v_add_f32_e32 v47, s12, v47
	v_add_f32_e32 v46, v46, v47
	v_mul_f32_e32 v47, v100, v39
	v_add_f32_e32 v46, 0x2b8cbccc, v46
	v_rsq_f32_e32 v46, v46
	v_mov_b32_dpp v47, v47 quad_perm:[1,0,3,2] row_mask:0xf bank_mask:0xf bound_ctrl:1
	v_fmac_f32_e32 v47, v100, v39
	v_fmac_f32_e32 v134, v53, v161
	s_nop 0
	v_add_f32_dpp v39, v47, v47 quad_perm:[2,3,0,1] row_mask:0xf bank_mask:0xf bound_ctrl:1
	v_fmac_f32_e32 v134, v54, v162
	v_fmac_f32_e32 v133, v44, v162
	v_add_f32_dpp v39, v39, v39 row_half_mirror row_mask:0xf bank_mask:0xf bound_ctrl:1
	v_fmac_f32_e32 v133, v45, v163
	v_fmac_f32_e32 v134, v55, v163
	v_add_f32_dpp v39, v39, v39 row_mirror row_mask:0xf bank_mask:0xf bound_ctrl:1
	s_nop 0
	v_readlane_b32 s55, v39, 0
	v_readlane_b32 s58, v39, 16
	v_readlane_b32 s59, v39, 32
	v_readlane_b32 s61, v39, 48
	v_mul_f32_e64 v39, v41, -v46
	ds_write2st64_b32 v34, v39, v38 offset0:6 offset1:7
	v_mul_f32_e64 v38, v40, -v39
	ds_write2st64_b32 v34, v38, v36 offset0:8 offset1:9
	ds_write2st64_b32 v34, v35, v37 offset0:10 offset1:11
	v_cvt_f32_f16_e32 v36, v108
	s_waitcnt vmcnt(2)
	v_cvt_f32_f16_e32 v35, v110
	s_waitcnt vmcnt(0)
	v_cvt_f32_ubyte0_e32 v39, v120
	v_mul_f32_e32 v40, 0x3b808081, v39
	v_mul_f32_e32 v41, v102, v36
	v_mul_f32_e32 v46, v41, v41
	v_fma_f32 v39, v39, s45, -1.0
	v_fma_f32 v39, v101, v39, 1.0
	v_mov_b32_dpp v46, v46 quad_perm:[1,0,3,2] row_mask:0xf bank_mask:0xf bound_ctrl:1
	v_fmac_f32_e32 v46, v41, v41
	v_mul_f32_e32 v36, v39, v36
	v_mul_f32_e32 v39, v36, v35
	v_add_f32_dpp v46, v46, v46 quad_perm:[2,3,0,1] row_mask:0xf bank_mask:0xf bound_ctrl:1
	v_cvt_f32_ubyte0_e32 v38, v119
	v_mul_f32_e32 v38, 0xbb1be179, v38
	v_add_f32_dpp v46, v46, v46 row_half_mirror row_mask:0xf bank_mask:0xf bound_ctrl:1
	v_mul_f32_e32 v38, 0x3fb8aa3b, v38
	v_exp_f32_e32 v38, v38
	v_add_f32_dpp v46, v46, v46 row_mirror row_mask:0xf bank_mask:0xf bound_ctrl:1
	s_waitcnt lgkmcnt(9)
	v_fmac_f32_e32 v133, v48, v164
	v_readlane_b32 s11, v46, 16
	v_readlane_b32 s13, v46, 48
	v_readlane_b32 s10, v46, 0
	v_readlane_b32 s12, v46, 32
	v_mov_b32_e32 v46, s11
	v_mov_b32_e32 v47, s13
	v_add_f32_e32 v46, s10, v46
	v_add_f32_e32 v47, s12, v47
	v_add_f32_e32 v46, v46, v47
	v_mul_f32_e32 v47, v100, v39
	v_add_f32_e32 v46, 0x2b8cbccc, v46
	v_rsq_f32_e32 v46, v46
	v_mov_b32_dpp v47, v47 quad_perm:[1,0,3,2] row_mask:0xf bank_mask:0xf bound_ctrl:1
	v_fmac_f32_e32 v47, v100, v39
	v_fmac_f32_e32 v134, v56, v164
	v_fmac_f32_e32 v133, v49, v165
	v_add_f32_dpp v39, v47, v47 quad_perm:[2,3,0,1] row_mask:0xf bank_mask:0xf bound_ctrl:1
	v_fmac_f32_e32 v134, v57, v165
	v_cvt_f32_f16_e32 v37, v111
	v_add_f32_dpp v39, v39, v39 row_half_mirror row_mask:0xf bank_mask:0xf bound_ctrl:1
	s_cmpk_lg_i32 s52, 0x5f
	s_cselect_b64 s[10:11], -1, 0
	v_add_f32_dpp v39, v39, v39 row_mirror row_mask:0xf bank_mask:0xf bound_ctrl:1
	v_fmac_f32_e32 v133, v50, v166
	v_fmac_f32_e32 v134, v58, v166
	v_readlane_b32 s68, v39, 0
	v_readlane_b32 s69, v39, 16
	v_readlane_b32 s71, v39, 32
	v_readlane_b32 s72, v39, 48
	v_mul_f32_e64 v39, v41, -v46
	ds_write2st64_b32 v34, v39, v38 offset0:12 offset1:13
	v_fmac_f32_e32 v133, v51, v167
	v_fmac_f32_e32 v134, v59, v167
	v_mul_f32_e64 v38, v40, -v39
	s_and_b64 s[12:13], s[0:1], s[10:11]
	v_add_f32_dpp v95, v95, v95 quad_perm:[1,0,3,2] row_mask:0xf bank_mask:0xf bound_ctrl:1
	v_add_f32_dpp v96, v96, v96 quad_perm:[1,0,3,2] row_mask:0xf bank_mask:0xf bound_ctrl:1
	v_add_f32_dpp v98, v98, v98 quad_perm:[1,0,3,2] row_mask:0xf bank_mask:0xf bound_ctrl:1
	v_add_f32_dpp v99, v99, v99 quad_perm:[1,0,3,2] row_mask:0xf bank_mask:0xf bound_ctrl:1
	v_add_f32_dpp v103, v103, v103 quad_perm:[1,0,3,2] row_mask:0xf bank_mask:0xf bound_ctrl:1
	v_add_f32_dpp v121, v121, v121 quad_perm:[1,0,3,2] row_mask:0xf bank_mask:0xf bound_ctrl:1
	v_add_f32_dpp v125, v125, v125 quad_perm:[1,0,3,2] row_mask:0xf bank_mask:0xf bound_ctrl:1
	v_add_f32_dpp v126, v126, v126 quad_perm:[1,0,3,2] row_mask:0xf bank_mask:0xf bound_ctrl:1
	v_add_f32_dpp v127, v127, v127 quad_perm:[1,0,3,2] row_mask:0xf bank_mask:0xf bound_ctrl:1
	v_add_f32_dpp v128, v128, v128 quad_perm:[1,0,3,2] row_mask:0xf bank_mask:0xf bound_ctrl:1
	v_add_f32_dpp v129, v129, v129 quad_perm:[1,0,3,2] row_mask:0xf bank_mask:0xf bound_ctrl:1
	v_add_f32_dpp v130, v130, v130 quad_perm:[1,0,3,2] row_mask:0xf bank_mask:0xf bound_ctrl:1
	v_add_f32_dpp v131, v131, v131 quad_perm:[1,0,3,2] row_mask:0xf bank_mask:0xf bound_ctrl:1
	v_add_f32_dpp v132, v132, v132 quad_perm:[1,0,3,2] row_mask:0xf bank_mask:0xf bound_ctrl:1
	v_add_f32_dpp v133, v133, v133 quad_perm:[1,0,3,2] row_mask:0xf bank_mask:0xf bound_ctrl:1
	v_add_f32_dpp v134, v134, v134 quad_perm:[1,0,3,2] row_mask:0xf bank_mask:0xf bound_ctrl:1
	v_add_f32_dpp v95, v95, v95 quad_perm:[2,3,0,1] row_mask:0xf bank_mask:0xf bound_ctrl:1
	v_add_f32_dpp v96, v96, v96 quad_perm:[2,3,0,1] row_mask:0xf bank_mask:0xf bound_ctrl:1
	v_add_f32_dpp v98, v98, v98 quad_perm:[2,3,0,1] row_mask:0xf bank_mask:0xf bound_ctrl:1
	v_add_f32_dpp v99, v99, v99 quad_perm:[2,3,0,1] row_mask:0xf bank_mask:0xf bound_ctrl:1
	v_add_f32_dpp v103, v103, v103 quad_perm:[2,3,0,1] row_mask:0xf bank_mask:0xf bound_ctrl:1
	v_add_f32_dpp v121, v121, v121 quad_perm:[2,3,0,1] row_mask:0xf bank_mask:0xf bound_ctrl:1
	v_add_f32_dpp v125, v125, v125 quad_perm:[2,3,0,1] row_mask:0xf bank_mask:0xf bound_ctrl:1
	v_add_f32_dpp v126, v126, v126 quad_perm:[2,3,0,1] row_mask:0xf bank_mask:0xf bound_ctrl:1
	v_add_f32_dpp v127, v127, v127 quad_perm:[2,3,0,1] row_mask:0xf bank_mask:0xf bound_ctrl:1
	v_add_f32_dpp v128, v128, v128 quad_perm:[2,3,0,1] row_mask:0xf bank_mask:0xf bound_ctrl:1
	v_add_f32_dpp v129, v129, v129 quad_perm:[2,3,0,1] row_mask:0xf bank_mask:0xf bound_ctrl:1
	v_add_f32_dpp v130, v130, v130 quad_perm:[2,3,0,1] row_mask:0xf bank_mask:0xf bound_ctrl:1
	v_add_f32_dpp v131, v131, v131 quad_perm:[2,3,0,1] row_mask:0xf bank_mask:0xf bound_ctrl:1
	v_add_f32_dpp v132, v132, v132 quad_perm:[2,3,0,1] row_mask:0xf bank_mask:0xf bound_ctrl:1
	v_add_f32_dpp v133, v133, v133 quad_perm:[2,3,0,1] row_mask:0xf bank_mask:0xf bound_ctrl:1
	v_add_f32_dpp v134, v134, v134 quad_perm:[2,3,0,1] row_mask:0xf bank_mask:0xf bound_ctrl:1
	v_add_f32_dpp v95, v95, v95 row_half_mirror row_mask:0xf bank_mask:0xf bound_ctrl:1
	v_add_f32_dpp v96, v96, v96 row_half_mirror row_mask:0xf bank_mask:0xf bound_ctrl:1
	v_add_f32_dpp v98, v98, v98 row_half_mirror row_mask:0xf bank_mask:0xf bound_ctrl:1
	v_add_f32_dpp v99, v99, v99 row_half_mirror row_mask:0xf bank_mask:0xf bound_ctrl:1
	v_add_f32_dpp v103, v103, v103 row_half_mirror row_mask:0xf bank_mask:0xf bound_ctrl:1
	v_add_f32_dpp v121, v121, v121 row_half_mirror row_mask:0xf bank_mask:0xf bound_ctrl:1
	v_add_f32_dpp v125, v125, v125 row_half_mirror row_mask:0xf bank_mask:0xf bound_ctrl:1
	v_add_f32_dpp v126, v126, v126 row_half_mirror row_mask:0xf bank_mask:0xf bound_ctrl:1
	v_add_f32_dpp v127, v127, v127 row_half_mirror row_mask:0xf bank_mask:0xf bound_ctrl:1
	v_add_f32_dpp v128, v128, v128 row_half_mirror row_mask:0xf bank_mask:0xf bound_ctrl:1
	v_add_f32_dpp v129, v129, v129 row_half_mirror row_mask:0xf bank_mask:0xf bound_ctrl:1
	v_add_f32_dpp v130, v130, v130 row_half_mirror row_mask:0xf bank_mask:0xf bound_ctrl:1
	v_add_f32_dpp v131, v131, v131 row_half_mirror row_mask:0xf bank_mask:0xf bound_ctrl:1
	v_add_f32_dpp v132, v132, v132 row_half_mirror row_mask:0xf bank_mask:0xf bound_ctrl:1
	v_add_f32_dpp v133, v133, v133 row_half_mirror row_mask:0xf bank_mask:0xf bound_ctrl:1
	v_add_f32_dpp v134, v134, v134 row_half_mirror row_mask:0xf bank_mask:0xf bound_ctrl:1
	ds_write2st64_b32 v34, v38, v36 offset0:14 offset1:15
	ds_write2st64_b32 v34, v35, v37 offset0:16 offset1:17
	s_and_saveexec_b64 s[10:11], s[12:13]
	s_cbranch_execz .LBB0_1081
	s_and_b64 vcc, exec, s[8:9]
	s_mov_b64 s[12:13], -1
	s_cbranch_vccnz .LBB0_1072
	v_sub_co_u32_e64 v34, s[12:13], s52, 63
	s_nop 0
	v_readfirstlane_b32 s63, v34
	s_lshr_b32 s63, s63, 4
	s_add_i32 s63, s63, 1
	s_and_b32 s73, s91, 15
	s_and_b64 s[12:13], s[12:13], exec
	s_cselect_b32 s70, 0, s63
	s_cselect_b32 s63, s91, s73
	s_mov_b64 s[12:13], 0

.LBB0_1124:
	s_add_i32 s11, s12, s83
	s_add_i32 s14, s12, s2
	s_cmp_lg_u32 s12, 0
	s_cselect_b64 s[8:9], -1, 0
	s_and_b64 s[12:13], s[8:9], exec
	s_cselect_b32 s14, s14, s82
	s_or_b64 s[8:9], s[20:21], s[8:9]
	s_and_b64 s[12:13], s[20:21], exec
	s_cselect_b32 s11, s11, s14
	s_and_b64 s[12:13], s[8:9], exec
	s_cselect_b32 s12, s84, 0x400
	s_lshl_b32 s10, s10, 4
	s_or_b32 s10, s10, s95
	s_xor_b32 s17, s10, -4
	s_and_b32 s13, s11, 1
	s_or_b32 s14, s10, 2
	s_xor_b32 s15, s10, -3
	s_or_b32 s16, s10, 3
	s_add_i32 s17, s17, s12
	s_cmp_eq_u32 s13, 0
	s_cselect_b32 s16, s16, s17
	s_add_i32 s15, s15, s12
	s_cmp_eq_u32 s13, 0
	s_cselect_b32 s14, s14, s15
	s_xor_b32 s17, s10, -2
	s_or_b32 s15, s10, 1
	s_add_i32 s17, s17, s12
	s_cmp_eq_u32 s13, 0
	s_cselect_b32 s15, s15, s17
	s_not_b32 s17, s10
	s_add_i32 s12, s12, s17
	s_cmp_eq_u32 s13, 0
	s_cselect_b32 s10, s10, s12
	s_ashr_i32 s12, s11, 6
	s_lshl_b32 s17, s12, 10
	s_addk_i32 s17, 0x2000
	s_lshl_b32 s12, s12, 8
	s_and_b64 s[8:9], s[8:9], exec
	v_lshrrev_b32_e32 v2, s36, v168
	s_cselect_b32 s12, s12, s17
	s_lshl_b32 s8, s11, 5
	v_mul_lo_u32 v2, s60, v2
	s_and_b32 s8, s8, 0x7c0
	v_bfe_u32 v3, v168, 0, s36
	v_lshlrev_b32_e32 v2, 5, v2
	v_or_b32_e32 v8, s8, v168
	v_readlane_b32 s64, v237, 2
	v_lshl_add_u32 v70, v3, 4, v2
	v_lshlrev_b32_e32 v2, 2, v8
	v_readlane_b32 s65, v237, 3
	s_lshl_b32 s34, s8, 1
	v_readlane_b32 s66, v237, 4
	v_readlane_b32 s67, v237, 5
	v_readlane_b32 s68, v237, 6
	v_readlane_b32 s69, v237, 7
	global_load_dword v102, v2, s[64:65]
	s_nop 1
	global_load_dword v101, v2, s[66:67]
	s_nop 0
	global_load_dword v100, v2, s[68:69]
	v_lshl_add_u64 v[2:3], v[76:77], 0, s[34:35]
	s_add_i32 s10, s12, s10
	s_mulk_i32 s13, 0x3000
	s_ashr_i32 s11, s10, 31
	ds_read_b128 v[138:141], v83 offset:12288
	ds_read_b128 v[26:29], v83 offset:12304
	v_mad_i64_i32 v[4:5], s[8:9], s10, v73, v[2:3]
	s_add_u32 s8, s10, s13
	global_load_ushort v109, v[4:5], off
	v_add_co_u32_e32 v4, vcc, s43, v4
	ds_read_b128 v[10:13], v83 offset:12544
	ds_read_b128 v[14:17], v83 offset:12560
	s_addc_u32 s9, s11, 0
	v_addc_co_u32_e32 v5, vcc, 0, v5, vcc
	s_lshl_b64 s[8:9], s[8:9], 11
	ds_read_b128 v[18:21], v83 offset:12800
	ds_read_b128 v[22:25], v83 offset:12816
	global_load_ushort v123, v[4:5], off offset:-4096
	global_load_ushort v124, v[4:5], off
	v_mov_b32_e32 v5, s9
	v_or_b32_e32 v4, s8, v8
	v_lshl_add_u64 v[6:7], s[22:23], 0, v[4:5]
	v_lshl_add_u64 v[4:5], s[24:25], 0, v[4:5]
	s_add_i32 s10, s12, s15
	global_load_ubyte v115, v[6:7], off
	global_load_ubyte v116, v[4:5], off
	s_ashr_i32 s11, s10, 31
	v_mad_i64_i32 v[4:5], s[8:9], s10, v73, v[2:3]
	s_add_u32 s8, s10, s13
	global_load_ushort v105, v[4:5], off
	v_add_co_u32_e32 v4, vcc, s43, v4
	s_addc_u32 s9, s11, 0
	s_nop 0
	v_addc_co_u32_e32 v5, vcc, 0, v5, vcc
	s_lshl_b64 s[8:9], s[8:9], 11
	global_load_ushort v117, v[4:5], off offset:-4096
	global_load_ushort v118, v[4:5], off
	v_mov_b32_e32 v5, s9
	ds_read_b128 v[142:145], v83 offset:13056
	ds_read_b128 v[30:33], v83 offset:13072
	v_or_b32_e32 v4, s8, v8
	v_lshl_add_u64 v[6:7], s[22:23], 0, v[4:5]
	v_lshl_add_u64 v[4:5], s[24:25], 0, v[4:5]
	s_add_i32 s10, s12, s14
	global_load_ubyte v113, v[6:7], off
	ds_read_b128 v[34:37], v83 offset:13312
	ds_read_b128 v[38:41], v83 offset:13328
	global_load_ubyte v114, v[4:5], off
	s_ashr_i32 s11, s10, 31
	v_mad_i64_i32 v[4:5], s[8:9], s10, v73, v[2:3]
	s_add_u32 s8, s10, s13
	global_load_ushort v104, v[4:5], off
	v_add_co_u32_e32 v4, vcc, s43, v4
	ds_read_b64 v[136:137], v82 offset:13568
	s_addc_u32 s9, s11, 0
	v_addc_co_u32_e32 v5, vcc, 0, v5, vcc
	s_lshl_b64 s[8:9], s[8:9], 11
	s_add_i32 s12, s12, s16
	global_load_ushort v106, v[4:5], off offset:-4096
	global_load_ushort v107, v[4:5], off
	v_mov_b32_e32 v5, s9
	v_or_b32_e32 v4, s8, v8
	s_ashr_i32 s10, s12, 31
	v_mad_i64_i32 v[2:3], s[8:9], s12, v73, v[2:3]
	v_lshl_add_u64 v[6:7], s[22:23], 0, v[4:5]
	v_lshl_add_u64 v[4:5], s[24:25], 0, v[4:5]
	s_add_u32 s8, s12, s13
	global_load_ubyte v112, v[6:7], off
	global_load_ubyte v122, v[4:5], off
	global_load_ushort v110, v[2:3], off
	v_add_co_u32_e32 v2, vcc, s43, v2
	s_addc_u32 s9, s10, 0
	s_nop 0
	v_addc_co_u32_e32 v3, vcc, 0, v3, vcc
	s_lshl_b64 s[8:9], s[8:9], 11
	global_load_ushort v108, v[2:3], off offset:-4096
	global_load_ushort v111, v[2:3], off
	v_mov_b32_e32 v3, s9
	v_or_b32_e32 v2, s8, v8
	v_lshl_add_u64 v[4:5], s[22:23], 0, v[2:3]
	v_lshl_add_u64 v[2:3], s[24:25], 0, v[2:3]
	global_load_ubyte v119, v[4:5], off
	global_load_ubyte v120, v[2:3], off
	s_waitcnt lgkmcnt(5)
	v_mul_f32_e32 v65, v42, v138
	v_mul_f32_e32 v138, v52, v138
	v_fmac_f32_e32 v65, v43, v139
	v_fmac_f32_e32 v138, v53, v139
	v_fmac_f32_e32 v65, v44, v140
	v_fmac_f32_e32 v138, v54, v140
	v_fmac_f32_e32 v65, v45, v141
	v_fmac_f32_e32 v138, v55, v141
	v_fmac_f32_e32 v65, v48, v26
	v_fmac_f32_e32 v138, v56, v26
	v_fmac_f32_e32 v65, v49, v27
	v_fmac_f32_e32 v138, v57, v27
	v_fmac_f32_e32 v65, v50, v28
	v_fmac_f32_e32 v138, v58, v28
	v_fmac_f32_e32 v65, v51, v29
	v_fmac_f32_e32 v138, v59, v29
	s_nop 0
	v_add_f32_dpp v65, v65, v65 quad_perm:[1,0,3,2] row_mask:0xf bank_mask:0xf bound_ctrl:1
	v_add_f32_dpp v138, v138, v138 quad_perm:[1,0,3,2] row_mask:0xf bank_mask:0xf bound_ctrl:1
	s_nop 0
	v_add_f32_dpp v65, v65, v65 quad_perm:[2,3,0,1] row_mask:0xf bank_mask:0xf bound_ctrl:1
	v_add_f32_dpp v138, v138, v138 quad_perm:[2,3,0,1] row_mask:0xf bank_mask:0xf bound_ctrl:1
	s_nop 0
	v_add_f32_dpp v65, v65, v65 row_half_mirror row_mask:0xf bank_mask:0xf bound_ctrl:1
	ds_read_b128 v[146:149], v83 offset:13824
	ds_read_b128 v[26:29], v83 offset:13840
	v_add_f32_dpp v138, v138, v138 row_half_mirror row_mask:0xf bank_mask:0xf bound_ctrl:1
	v_mul_f32_e32 v64, v22, v65
	v_fmac_f32_e32 v64, v48, v14
	v_mul_f32_e32 v48, v23, v65
	v_fmac_f32_e32 v48, v49, v15
	ds_read_b128 v[150:153], v83 offset:14080
	ds_read_b128 v[6:9], v83 offset:14096
	v_mul_f32_e32 v49, v24, v65
	v_fmac_f32_e32 v49, v50, v16
	v_mul_f32_e32 v50, v25, v65
	v_fmac_f32_e32 v50, v51, v17
	v_mul_f32_e32 v60, v18, v65
	ds_read_b128 v[154:157], v83 offset:14336
	ds_read_b128 v[158:161], v83 offset:14352
	v_mul_f32_e32 v51, v18, v138
	v_fmac_f32_e32 v60, v42, v10
	v_mul_f32_e32 v61, v19, v65
	v_mul_f32_e32 v62, v20, v65
	v_mul_f32_e32 v63, v21, v65
	v_fmac_f32_e32 v51, v52, v10
	v_mul_f32_e32 v65, v19, v138
	v_fmac_f32_e32 v61, v43, v11
	s_waitcnt lgkmcnt(6)
	v_fmac_f32_e32 v60, v136, v142
	v_fmac_f32_e32 v62, v44, v12
	v_fmac_f32_e32 v63, v45, v13
	v_fmac_f32_e32 v51, v137, v142
	v_fmac_f32_e32 v65, v53, v11
	v_mul_f32_e32 v66, v20, v138
	v_fmac_f32_e32 v61, v136, v143
	v_fmac_f32_e32 v62, v136, v144
	v_fmac_f32_e32 v63, v136, v145
	v_fmac_f32_e32 v64, v136, v30
	v_fmac_f32_e32 v48, v136, v31
	v_fmac_f32_e32 v49, v136, v32
	v_fmac_f32_e32 v50, v136, v33
	v_mul_f32_e32 v135, v34, v60
	v_fmac_f32_e32 v65, v137, v143
	v_fmac_f32_e32 v66, v54, v12
	v_mul_f32_e32 v67, v21, v138
	v_mul_f32_e32 v136, v34, v51
	v_fmac_f32_e32 v66, v137, v144
	v_fmac_f32_e32 v135, v61, v35
	v_fmac_f32_e32 v67, v55, v13
	v_mul_f32_e32 v68, v22, v138
	v_fmac_f32_e32 v136, v65, v35
	v_fmac_f32_e32 v67, v137, v145
	v_fmac_f32_e32 v135, v62, v36
	v_fmac_f32_e32 v68, v56, v14
	v_mul_f32_e32 v69, v23, v138
	v_fmac_f32_e32 v136, v66, v36
	ds_read_b128 v[10:13], v83 offset:14592
	ds_read_b128 v[18:21], v83 offset:14608
	ds_read_b128 v[162:165], v83 offset:14848
	ds_read_b128 v[178:181], v83 offset:14864
	v_fmac_f32_e32 v68, v137, v30
	v_fmac_f32_e32 v135, v63, v37
	v_fmac_f32_e32 v69, v57, v15
	v_mul_f32_e32 v80, v24, v138
	v_fmac_f32_e32 v136, v67, v37
	v_fmac_f32_e32 v69, v137, v31
	v_fmac_f32_e32 v135, v64, v38
	v_fmac_f32_e32 v80, v58, v16
	v_mul_f32_e32 v81, v25, v138
	ds_read_b64 v[138:139], v82 offset:15104
	v_fmac_f32_e32 v136, v68, v38
	v_fmac_f32_e32 v80, v137, v32
	v_fmac_f32_e32 v135, v48, v39
	v_fmac_f32_e32 v81, v59, v17
	ds_read_b128 v[188:191], v83 offset:15360
	ds_read_b128 v[42:45], v83 offset:15376
	v_fmac_f32_e32 v136, v69, v39
	v_fmac_f32_e32 v81, v137, v33
	v_fmac_f32_e32 v135, v49, v40
	v_fmac_f32_e32 v136, v80, v40
	global_load_dwordx4 v[2:5], v70, s[38:39]
	v_fmac_f32_e32 v135, v50, v41
	s_waitcnt lgkmcnt(11)
	v_mul_f32_e32 v59, v60, v146
	v_mul_f32_e32 v146, v51, v146
	v_fmac_f32_e32 v59, v61, v147
	v_fmac_f32_e32 v146, v65, v147
	v_fmac_f32_e32 v59, v62, v148
	v_fmac_f32_e32 v146, v66, v148
	v_fmac_f32_e32 v59, v63, v149
	v_fmac_f32_e32 v146, v67, v149
	v_fmac_f32_e32 v59, v64, v26
	v_fmac_f32_e32 v146, v68, v26
	s_mov_b32 s61, s35
	v_fmac_f32_e32 v59, v48, v27
	v_fmac_f32_e32 v146, v69, v27
	v_fmac_f32_e32 v59, v49, v28
	v_fmac_f32_e32 v146, v80, v28
	v_fmac_f32_e32 v59, v50, v29
	v_fmac_f32_e32 v146, v81, v29
	s_nop 0
	v_add_f32_dpp v59, v59, v59 quad_perm:[1,0,3,2] row_mask:0xf bank_mask:0xf bound_ctrl:1
	v_add_f32_dpp v146, v146, v146 quad_perm:[1,0,3,2] row_mask:0xf bank_mask:0xf bound_ctrl:1
	v_fmac_f32_e32 v136, v81, v41
	v_add_f32_dpp v59, v59, v59 quad_perm:[2,3,0,1] row_mask:0xf bank_mask:0xf bound_ctrl:1
	v_add_f32_dpp v146, v146, v146 quad_perm:[2,3,0,1] row_mask:0xf bank_mask:0xf bound_ctrl:1
	ds_read_b128 v[194:197], v83 offset:15616
	ds_read_b128 v[202:205], v83 offset:15632
	ds_read_b128 v[34:37], v83 offset:15872
	ds_read_b128 v[14:17], v83 offset:15888
	v_add_f32_dpp v59, v59, v59 row_half_mirror row_mask:0xf bank_mask:0xf bound_ctrl:1
	v_add_f32_dpp v146, v146, v146 row_half_mirror row_mask:0xf bank_mask:0xf bound_ctrl:1
	v_lshl_add_u64 v[46:47], s[38:39], 0, v[70:71]
	s_waitcnt lgkmcnt(11)
	v_mul_f32_e32 v52, v154, v59
	v_fmac_f32_e32 v52, v60, v150
	v_mul_f32_e32 v53, v155, v59
	v_mul_f32_e32 v54, v156, v59
	v_mul_f32_e32 v55, v157, v59
	v_mul_f32_e32 v56, v158, v59
	v_mul_f32_e32 v57, v159, v59
	v_mul_f32_e32 v58, v160, v59
	v_mul_f32_e32 v59, v161, v59
	v_mul_f32_e32 v60, v154, v146
	s_lshl_b64 s[8:9], s[60:61], 2
	v_fmac_f32_e32 v60, v51, v150
	v_fmac_f32_e32 v59, v50, v9
	v_mul_f32_e32 v142, v158, v146
	v_mul_f32_e32 v143, v159, v146
	v_mul_f32_e32 v144, v160, v146
	v_mul_f32_e32 v145, v161, v146
	v_lshl_add_u64 v[50:51], v[46:47], 0, s[8:9]
	v_fmac_f32_e32 v53, v61, v151
	v_fmac_f32_e32 v54, v62, v152
	v_fmac_f32_e32 v56, v64, v6
	v_fmac_f32_e32 v57, v48, v7
	v_fmac_f32_e32 v58, v49, v8
	v_mul_f32_e32 v61, v155, v146
	v_mul_f32_e32 v62, v156, v146
	v_mul_f32_e32 v140, v157, v146
	v_fmac_f32_e32 v142, v68, v6
	v_fmac_f32_e32 v143, v69, v7
	v_fmac_f32_e32 v144, v80, v8
	v_fmac_f32_e32 v145, v81, v9
	global_load_dwordx4 v[6:9], v[50:51], off
	v_fmac_f32_e32 v61, v65, v151
	s_waitcnt lgkmcnt(5)
	v_fmac_f32_e32 v52, v138, v10
	v_fmac_f32_e32 v60, v139, v10
	ds_read_b128 v[38:41], v83 offset:16128
	ds_read_b128 v[22:25], v83 offset:16144
	v_fmac_f32_e32 v62, v66, v152
	v_fmac_f32_e32 v53, v138, v11
	v_fmac_f32_e32 v55, v63, v153
	v_fmac_f32_e32 v61, v139, v11
	v_mul_f32_e32 v63, v52, v188
	v_mul_f32_e32 v188, v60, v188
	v_fmac_f32_e32 v140, v67, v153
	v_fmac_f32_e32 v54, v138, v12
	v_fmac_f32_e32 v62, v139, v12
	v_fmac_f32_e32 v63, v53, v189
	v_fmac_f32_e32 v188, v61, v189
	v_fmac_f32_e32 v55, v138, v13
	v_fmac_f32_e32 v56, v138, v18
	v_fmac_f32_e32 v57, v138, v19
	ds_read_b128 v[30:33], v83 offset:16384
	ds_read_b128 v[26:29], v83 offset:16400
	ds_read_b64 v[146:147], v82 offset:16640
	v_fmac_f32_e32 v58, v138, v20
	v_fmac_f32_e32 v59, v138, v21
	v_mul_f32_e32 v137, v162, v52
	v_fmac_f32_e32 v140, v139, v13
	v_mul_f32_e32 v138, v162, v60
	v_fmac_f32_e32 v142, v139, v18
	v_fmac_f32_e32 v63, v54, v190
	v_fmac_f32_e32 v188, v62, v190
	v_fmac_f32_e32 v137, v53, v163
	v_fmac_f32_e32 v143, v139, v19
	v_fmac_f32_e32 v144, v139, v20
	ds_read_b128 v[154:157], v83 offset:16896
	ds_read_b128 v[46:49], v83 offset:16912
	v_fmac_f32_e32 v145, v139, v21
	v_fmac_f32_e32 v138, v61, v163
	v_fmac_f32_e32 v63, v55, v191
	v_fmac_f32_e32 v188, v140, v191
	v_fmac_f32_e32 v137, v54, v164
	v_fmac_f32_e32 v138, v62, v164
	s_waitcnt lgkmcnt(7)
	v_fmac_f32_e32 v63, v56, v42
	v_fmac_f32_e32 v188, v142, v42
	v_fmac_f32_e32 v137, v55, v165
	v_fmac_f32_e32 v138, v140, v165
	v_fmac_f32_e32 v63, v57, v43
	v_fmac_f32_e32 v188, v143, v43
	v_fmac_f32_e32 v137, v56, v178
	v_fmac_f32_e32 v138, v142, v178
	v_fmac_f32_e32 v63, v58, v44
	v_fmac_f32_e32 v188, v144, v44
	v_fmac_f32_e32 v137, v57, v179
	v_fmac_f32_e32 v138, v143, v179
	v_fmac_f32_e32 v63, v59, v45
	v_fmac_f32_e32 v188, v145, v45
	v_fmac_f32_e32 v137, v58, v180
	v_add_f32_dpp v63, v63, v63 quad_perm:[1,0,3,2] row_mask:0xf bank_mask:0xf bound_ctrl:1
	v_add_f32_dpp v188, v188, v188 quad_perm:[1,0,3,2] row_mask:0xf bank_mask:0xf bound_ctrl:1
	s_nop 0
	v_add_f32_dpp v63, v63, v63 quad_perm:[2,3,0,1] row_mask:0xf bank_mask:0xf bound_ctrl:1
	v_add_f32_dpp v188, v188, v188 quad_perm:[2,3,0,1] row_mask:0xf bank_mask:0xf bound_ctrl:1
	v_fmac_f32_e32 v138, v144, v180
	v_add_f32_dpp v63, v63, v63 row_half_mirror row_mask:0xf bank_mask:0xf bound_ctrl:1
	v_add_f32_dpp v188, v188, v188 row_half_mirror row_mask:0xf bank_mask:0xf bound_ctrl:1
	v_fmac_f32_e32 v137, v59, v181
	v_mul_f32_e32 v80, v36, v63
	v_mul_f32_e32 v70, v37, v63
	v_mul_f32_e32 v67, v16, v63
	v_mul_f32_e32 v66, v17, v63
	v_mul_f32_e32 v65, v34, v188
	v_mul_f32_e32 v64, v35, v188
	v_fmac_f32_e32 v138, v145, v181
	v_mul_f32_e32 v141, v34, v63
	ds_read_b128 v[158:161], v83 offset:17152
	ds_read_b128 v[162:165], v83 offset:17168
	ds_read_b128 v[178:181], v83 offset:17408
	ds_read_b128 v[206:209], v83 offset:17424
	v_mul_f32_e32 v81, v35, v63
	v_fmac_f32_e32 v80, v54, v196
	v_fmac_f32_e32 v70, v55, v197
	v_mul_f32_e32 v69, v14, v63
	v_mul_f32_e32 v68, v15, v63
	v_fmac_f32_e32 v67, v58, v204
	v_fmac_f32_e32 v66, v59, v205
	v_fmac_f32_e32 v65, v60, v194
	v_fmac_f32_e32 v64, v61, v195
	ds_read_b128 v[42:45], v83 offset:17664
	ds_read_b128 v[212:215], v83 offset:17680
	v_mul_f32_e32 v63, v36, v188
	v_mul_f32_e32 v61, v14, v188
	ds_read_b128 v[220:223], v83 offset:17920
	ds_read_b128 v[18:21], v83 offset:17936
	v_mul_f32_e32 v60, v15, v188
	v_mul_f32_e32 v59, v16, v188
	v_mul_f32_e32 v58, v17, v188
	v_lshl_add_u64 v[54:55], v[50:51], 0, s[8:9]
	v_fmac_f32_e32 v141, v52, v194
	v_fmac_f32_e32 v81, v53, v195
	v_fmac_f32_e32 v69, v56, v202
	v_fmac_f32_e32 v68, v57, v203
	v_fmac_f32_e32 v63, v62, v196
	v_mul_f32_e32 v62, v37, v188
	v_fmac_f32_e32 v61, v142, v202
	v_fmac_f32_e32 v60, v143, v203
	ds_read_b64 v[56:57], v82 offset:18176
	v_fmac_f32_e32 v59, v144, v204
	v_fmac_f32_e32 v58, v145, v205
	global_load_dwordx4 v[10:13], v[54:55], off
	v_fmac_f32_e32 v62, v140, v197
	s_waitcnt lgkmcnt(10)
	v_fmac_f32_e32 v141, v146, v38
	v_fmac_f32_e32 v65, v147, v38
	v_fmac_f32_e32 v81, v146, v39
	v_mul_f32_e32 v139, v30, v141
	v_fmac_f32_e32 v64, v147, v39
	v_mul_f32_e32 v140, v30, v65
	v_mul_f32_e32 v142, v141, v154
	v_fmac_f32_e32 v80, v146, v40
	v_fmac_f32_e32 v139, v81, v31
	v_fmac_f32_e32 v63, v147, v40
	v_fmac_f32_e32 v140, v64, v31
	v_mul_f32_e32 v154, v65, v154
	v_fmac_f32_e32 v70, v146, v41
	v_fmac_f32_e32 v139, v80, v32
	v_fmac_f32_e32 v62, v147, v41
	v_fmac_f32_e32 v140, v63, v32
	v_fmac_f32_e32 v142, v81, v155
	v_fmac_f32_e32 v154, v64, v155
	v_fmac_f32_e32 v69, v146, v22
	v_fmac_f32_e32 v139, v70, v33
	v_fmac_f32_e32 v61, v147, v22
	v_fmac_f32_e32 v140, v62, v33
	v_fmac_f32_e32 v142, v80, v156
	v_fmac_f32_e32 v154, v63, v156
	v_fmac_f32_e32 v68, v146, v23
	v_fmac_f32_e32 v139, v69, v26
	v_fmac_f32_e32 v60, v147, v23
	v_fmac_f32_e32 v140, v61, v26
	v_fmac_f32_e32 v67, v146, v24
	v_fmac_f32_e32 v142, v70, v157
	v_fmac_f32_e32 v154, v62, v157
	v_fmac_f32_e32 v66, v146, v25
	v_fmac_f32_e32 v139, v68, v27
	v_fmac_f32_e32 v59, v147, v24
	v_fmac_f32_e32 v58, v147, v25
	v_fmac_f32_e32 v140, v60, v27
	s_waitcnt lgkmcnt(6)
	v_fmac_f32_e32 v142, v69, v46
	v_fmac_f32_e32 v154, v61, v46
	v_fmac_f32_e32 v139, v67, v28
	v_fmac_f32_e32 v140, v59, v28
	v_fmac_f32_e32 v142, v68, v47
	v_fmac_f32_e32 v154, v60, v47
	v_fmac_f32_e32 v139, v66, v29
	v_fmac_f32_e32 v142, v67, v48
	v_fmac_f32_e32 v154, v59, v48
	v_fmac_f32_e32 v142, v66, v49
	v_fmac_f32_e32 v154, v58, v49
	s_nop 0
	v_add_f32_dpp v142, v142, v142 quad_perm:[1,0,3,2] row_mask:0xf bank_mask:0xf bound_ctrl:1
	v_add_f32_dpp v154, v154, v154 quad_perm:[1,0,3,2] row_mask:0xf bank_mask:0xf bound_ctrl:1
	s_nop 0
	v_add_f32_dpp v142, v142, v142 quad_perm:[2,3,0,1] row_mask:0xf bank_mask:0xf bound_ctrl:1
	v_add_f32_dpp v154, v154, v154 quad_perm:[2,3,0,1] row_mask:0xf bank_mask:0xf bound_ctrl:1
	v_fmac_f32_e32 v140, v58, v29
	v_add_f32_dpp v142, v142, v142 row_half_mirror row_mask:0xf bank_mask:0xf bound_ctrl:1
	v_add_f32_dpp v154, v154, v154 row_half_mirror row_mask:0xf bank_mask:0xf bound_ctrl:1
	ds_read_b128 v[188:191], v83 offset:18432
	ds_read_b128 v[24:27], v83 offset:18448
	v_mul_f32_e32 v143, v178, v142
	v_mul_f32_e32 v144, v179, v142
	v_mul_f32_e32 v148, v178, v154
	v_fmac_f32_e32 v143, v141, v158
	ds_read_b128 v[28:31], v83 offset:18688
	ds_read_b128 v[32:35], v83 offset:18704
	v_fmac_f32_e32 v144, v81, v159
	v_mul_f32_e32 v81, v180, v142
	v_fmac_f32_e32 v148, v65, v158
	v_mul_f32_e32 v149, v179, v154
	ds_read_b128 v[36:39], v83 offset:18944
	ds_read_b128 v[194:197], v83 offset:18960
	v_fmac_f32_e32 v149, v64, v159
	ds_read_b128 v[156:159], v83 offset:19200
	ds_read_b128 v[48:51], v83 offset:19216
	s_waitcnt lgkmcnt(8)
	v_fmac_f32_e32 v143, v56, v42
	v_fmac_f32_e32 v81, v80, v160
	v_mul_f32_e32 v80, v181, v142
	v_fmac_f32_e32 v148, v57, v42
	v_mul_f32_e32 v150, v180, v154
	v_fmac_f32_e32 v80, v70, v161
	v_fmac_f32_e32 v144, v56, v43
	v_mul_f32_e32 v70, v206, v142
	v_mul_f32_e32 v145, v207, v142
	ds_read_b128 v[202:205], v83 offset:19456
	v_mul_f32_e32 v146, v208, v142
	ds_read_b128 v[224:227], v83 offset:19472
	v_mul_f32_e32 v147, v209, v142
	v_mul_f32_e32 v141, v220, v143
	v_fmac_f32_e32 v149, v57, v43
	v_fmac_f32_e32 v150, v63, v160
	v_mul_f32_e32 v63, v181, v154
	v_mul_f32_e32 v142, v220, v148
	v_fmac_f32_e32 v63, v62, v161
	v_fmac_f32_e32 v81, v56, v44
	v_fmac_f32_e32 v141, v144, v221
	v_fmac_f32_e32 v150, v57, v44
	v_mul_f32_e32 v62, v206, v154
	v_fmac_f32_e32 v142, v149, v221
	v_mul_f32_e32 v151, v207, v154
	v_fmac_f32_e32 v80, v56, v45
	v_fmac_f32_e32 v70, v69, v162
	v_fmac_f32_e32 v141, v81, v222
	v_fmac_f32_e32 v63, v57, v45
	v_fmac_f32_e32 v62, v61, v162
	v_fmac_f32_e32 v142, v150, v222
	ds_read_b64 v[22:23], v82 offset:19712
	v_mul_f32_e32 v152, v208, v154
	v_fmac_f32_e32 v70, v56, v212
	v_fmac_f32_e32 v145, v68, v163
	v_fmac_f32_e32 v141, v80, v223
	v_fmac_f32_e32 v62, v57, v212
	v_fmac_f32_e32 v151, v60, v163
	v_fmac_f32_e32 v142, v63, v223
	v_mul_f32_e32 v153, v209, v154
	v_fmac_f32_e32 v145, v56, v213
	v_fmac_f32_e32 v146, v67, v164
	v_fmac_f32_e32 v141, v70, v18
	v_fmac_f32_e32 v151, v57, v213
	v_fmac_f32_e32 v152, v59, v164
	v_fmac_f32_e32 v142, v62, v18
	v_fmac_f32_e32 v147, v66, v165
	v_fmac_f32_e32 v146, v56, v214
	v_fmac_f32_e32 v141, v145, v19
	v_fmac_f32_e32 v152, v57, v214
	v_fmac_f32_e32 v153, v58, v165
	v_fmac_f32_e32 v142, v151, v19
	v_fmac_f32_e32 v147, v56, v215
	v_fmac_f32_e32 v141, v146, v20
	v_fmac_f32_e32 v153, v57, v215
	v_fmac_f32_e32 v142, v152, v20
	v_lshl_add_u64 v[18:19], v[54:55], 0, s[8:9]
	global_load_dwordx4 v[14:17], v[18:19], off
	v_fmac_f32_e32 v141, v147, v21
	s_waitcnt lgkmcnt(5)
	v_mul_f32_e32 v154, v143, v188
	v_mul_f32_e32 v188, v148, v188
	v_fmac_f32_e32 v154, v144, v189
	v_fmac_f32_e32 v188, v149, v189
	v_fmac_f32_e32 v154, v81, v190
	v_fmac_f32_e32 v188, v150, v190
	v_fmac_f32_e32 v154, v80, v191
	v_fmac_f32_e32 v188, v63, v191
	v_fmac_f32_e32 v154, v70, v24
	v_fmac_f32_e32 v188, v62, v24
	v_fmac_f32_e32 v154, v145, v25
	v_fmac_f32_e32 v188, v151, v25
	v_fmac_f32_e32 v154, v146, v26
	v_fmac_f32_e32 v188, v152, v26
	v_fmac_f32_e32 v154, v147, v27
	v_fmac_f32_e32 v188, v153, v27
	s_nop 0
	v_add_f32_dpp v154, v154, v154 quad_perm:[1,0,3,2] row_mask:0xf bank_mask:0xf bound_ctrl:1
	v_add_f32_dpp v188, v188, v188 quad_perm:[1,0,3,2] row_mask:0xf bank_mask:0xf bound_ctrl:1
	s_nop 0
	v_add_f32_dpp v154, v154, v154 quad_perm:[2,3,0,1] row_mask:0xf bank_mask:0xf bound_ctrl:1
	v_add_f32_dpp v188, v188, v188 quad_perm:[2,3,0,1] row_mask:0xf bank_mask:0xf bound_ctrl:1
	v_fmac_f32_e32 v142, v153, v21
	v_add_f32_dpp v154, v154, v154 row_half_mirror row_mask:0xf bank_mask:0xf bound_ctrl:1
	v_add_f32_dpp v188, v188, v188 row_half_mirror row_mask:0xf bank_mask:0xf bound_ctrl:1
	ds_read_b128 v[58:61], v83 offset:19968
	ds_read_b128 v[54:57], v83 offset:19984
	v_mul_f32_e32 v66, v38, v154
	v_mul_f32_e32 v68, v194, v154
	v_mul_f32_e32 v64, v36, v154
	ds_read_b128 v[178:181], v83 offset:20224
	ds_read_b128 v[206:209], v83 offset:20240
	v_fmac_f32_e32 v66, v81, v30
	v_mul_f32_e32 v67, v39, v154
	v_fmac_f32_e32 v68, v70, v32
	v_mul_f32_e32 v70, v196, v154
	ds_read_b128 v[212:215], v83 offset:20480
	ds_read_b128 v[220:223], v83 offset:20496
	v_mul_f32_e32 v81, v36, v188
	v_fmac_f32_e32 v64, v143, v28
	v_mul_f32_e32 v65, v37, v154
	ds_read_b128 v[228:231], v83 offset:20736
	ds_read_b128 v[238:241], v83 offset:20752
	v_fmac_f32_e32 v67, v80, v31
	v_fmac_f32_e32 v70, v146, v34
	v_mul_f32_e32 v80, v197, v154
	v_fmac_f32_e32 v81, v148, v28
	v_mul_f32_e32 v146, v37, v188
	v_fmac_f32_e32 v65, v144, v29
	s_waitcnt lgkmcnt(8)
	v_fmac_f32_e32 v64, v22, v156
	v_fmac_f32_e32 v80, v147, v35
	v_fmac_f32_e32 v81, v23, v156
	v_fmac_f32_e32 v146, v149, v29
	v_mul_f32_e32 v147, v38, v188
	v_fmac_f32_e32 v65, v22, v157
	v_mul_f32_e32 v143, v202, v64
	v_fmac_f32_e32 v146, v23, v157
	v_fmac_f32_e32 v147, v150, v30
	v_mul_f32_e32 v148, v39, v188
	v_mul_f32_e32 v144, v202, v81
	v_fmac_f32_e32 v148, v63, v31
	v_fmac_f32_e32 v66, v22, v158
	v_fmac_f32_e32 v143, v65, v203
	ds_read_b128 v[42:45], v83 offset:20992
	ds_read_b128 v[38:41], v83 offset:21008
	ds_read_b64 v[160:161], v82 offset:21248
	v_fmac_f32_e32 v147, v23, v158
	v_mul_f32_e32 v149, v194, v188
	v_fmac_f32_e32 v144, v146, v203
	v_fmac_f32_e32 v149, v62, v32
	v_fmac_f32_e32 v67, v22, v159
	v_mul_f32_e32 v69, v195, v154
	v_fmac_f32_e32 v143, v66, v204
	v_fmac_f32_e32 v148, v23, v159
	v_mul_f32_e32 v150, v195, v188
	v_fmac_f32_e32 v144, v147, v204
	v_fmac_f32_e32 v69, v145, v33
	v_fmac_f32_e32 v68, v22, v48
	v_fmac_f32_e32 v143, v67, v205
	v_fmac_f32_e32 v149, v23, v48
	v_fmac_f32_e32 v150, v151, v33
	v_mul_f32_e32 v151, v196, v188
	v_fmac_f32_e32 v144, v148, v205
	v_fmac_f32_e32 v69, v22, v49
	v_fmac_f32_e32 v143, v68, v224
	v_fmac_f32_e32 v150, v23, v49
	v_fmac_f32_e32 v151, v152, v34
	v_mul_f32_e32 v152, v197, v188
	v_fmac_f32_e32 v144, v149, v224
	v_fmac_f32_e32 v152, v153, v35
	v_fmac_f32_e32 v70, v22, v50
	v_fmac_f32_e32 v143, v69, v225
	v_fmac_f32_e32 v151, v23, v50
	v_fmac_f32_e32 v144, v150, v225
	v_lshl_add_u64 v[62:63], v[18:19], 0, s[8:9]
	v_fmac_f32_e32 v80, v22, v51
	v_fmac_f32_e32 v143, v70, v226
	v_fmac_f32_e32 v152, v23, v51
	v_fmac_f32_e32 v144, v151, v226
	global_load_dwordx4 v[18:21], v[62:63], off
	v_fmac_f32_e32 v143, v80, v227
	ds_read_b128 v[188:191], v83 offset:21504
	ds_read_b128 v[46:49], v83 offset:21520
	s_waitcnt lgkmcnt(7)
	v_mul_f32_e32 v145, v64, v58
	v_mul_f32_e32 v58, v81, v58
	v_fmac_f32_e32 v145, v65, v59
	v_fmac_f32_e32 v58, v146, v59
	v_fmac_f32_e32 v145, v66, v60
	v_fmac_f32_e32 v58, v147, v60
	v_fmac_f32_e32 v145, v67, v61
	v_fmac_f32_e32 v58, v148, v61
	v_fmac_f32_e32 v145, v68, v54
	v_fmac_f32_e32 v58, v149, v54
	v_fmac_f32_e32 v145, v69, v55
	v_fmac_f32_e32 v58, v150, v55
	v_fmac_f32_e32 v145, v70, v56
	v_fmac_f32_e32 v58, v151, v56
	v_fmac_f32_e32 v145, v80, v57
	v_fmac_f32_e32 v58, v152, v57
	s_nop 0
	v_add_f32_dpp v145, v145, v145 quad_perm:[1,0,3,2] row_mask:0xf bank_mask:0xf bound_ctrl:1
	v_add_f32_dpp v58, v58, v58 quad_perm:[1,0,3,2] row_mask:0xf bank_mask:0xf bound_ctrl:1
	s_nop 0
	v_add_f32_dpp v145, v145, v145 quad_perm:[2,3,0,1] row_mask:0xf bank_mask:0xf bound_ctrl:1
	v_add_f32_dpp v58, v58, v58 quad_perm:[2,3,0,1] row_mask:0xf bank_mask:0xf bound_ctrl:1
	v_fmac_f32_e32 v144, v152, v227
	v_add_f32_dpp v145, v145, v145 row_half_mirror row_mask:0xf bank_mask:0xf bound_ctrl:1
	v_add_f32_dpp v58, v58, v58 row_half_mirror row_mask:0xf bank_mask:0xf bound_ctrl:1
	ds_read_b128 v[34:37], v83 offset:21760
	ds_read_b128 v[26:29], v83 offset:21776
	ds_read_b128 v[50:53], v83 offset:22016
	ds_read_b128 v[30:33], v83 offset:22032
	v_mul_f32_e32 v157, v220, v145
	v_fmac_f32_e32 v157, v68, v206
	v_mul_f32_e32 v68, v221, v145
	v_mul_f32_e32 v153, v212, v145
	v_mul_f32_e32 v154, v213, v145
	v_mul_f32_e32 v155, v214, v145
	v_mul_f32_e32 v156, v215, v145
	v_fmac_f32_e32 v68, v69, v207
	v_mul_f32_e32 v69, v222, v145
	v_mul_f32_e32 v158, v223, v145
	v_fmac_f32_e32 v153, v64, v178
	v_fmac_f32_e32 v154, v65, v179
	v_fmac_f32_e32 v155, v66, v180
	v_fmac_f32_e32 v156, v67, v181
	v_fmac_f32_e32 v69, v70, v208
	v_fmac_f32_e32 v158, v80, v209
	s_waitcnt lgkmcnt(6)
	v_fmac_f32_e32 v153, v160, v228
	ds_read_b128 v[54:57], v83 offset:22272
	v_fmac_f32_e32 v154, v160, v229
	ds_read_b128 v[194:197], v83 offset:22288
	v_fmac_f32_e32 v155, v160, v230
	v_fmac_f32_e32 v156, v160, v231
	v_fmac_f32_e32 v157, v160, v238
	v_fmac_f32_e32 v68, v160, v239
	v_fmac_f32_e32 v69, v160, v240
	v_fmac_f32_e32 v158, v160, v241
	v_mul_f32_e32 v160, v215, v58
	v_mul_f32_e32 v80, v212, v58
	v_fmac_f32_e32 v160, v148, v181
	v_mul_f32_e32 v148, v220, v58
	ds_read_b128 v[202:205], v83 offset:22528
	ds_read_b128 v[224:227], v83 offset:22544
	v_mul_f32_e32 v162, v221, v58
	v_mul_f32_e32 v163, v222, v58
	v_mul_f32_e32 v164, v223, v58
	v_lshl_add_u64 v[66:67], v[62:63], 0, s[8:9]
	v_fmac_f32_e32 v80, v81, v178
	v_mul_f32_e32 v81, v213, v58
	v_mul_f32_e32 v159, v214, v58
	v_fmac_f32_e32 v148, v149, v206
	v_fmac_f32_e32 v162, v150, v207
	v_fmac_f32_e32 v163, v151, v208
	v_fmac_f32_e32 v164, v152, v209
	ds_read_b64 v[166:167], v82 offset:22784
	global_load_dwordx4 v[22:25], v[66:67], off
	v_fmac_f32_e32 v81, v146, v179
	v_fmac_f32_e32 v80, v161, v228
	v_fmac_f32_e32 v81, v161, v229
	v_fmac_f32_e32 v159, v147, v180
	s_waitcnt lgkmcnt(9)
	v_mul_f32_e32 v147, v153, v188
	v_mul_f32_e32 v188, v80, v188
	v_fmac_f32_e32 v159, v161, v230
	v_mul_f32_e32 v145, v42, v153
	v_mul_f32_e32 v146, v42, v80
	v_fmac_f32_e32 v160, v161, v231
	v_fmac_f32_e32 v147, v154, v189
	v_fmac_f32_e32 v188, v81, v189
	v_fmac_f32_e32 v145, v154, v43
	v_fmac_f32_e32 v146, v81, v43
	v_fmac_f32_e32 v148, v161, v238
	v_fmac_f32_e32 v147, v155, v190
	v_fmac_f32_e32 v188, v159, v190
	v_fmac_f32_e32 v145, v155, v44
	v_fmac_f32_e32 v146, v159, v44
	v_fmac_f32_e32 v162, v161, v239
	v_fmac_f32_e32 v147, v156, v191
	v_fmac_f32_e32 v188, v160, v191
	v_fmac_f32_e32 v145, v156, v45
	v_fmac_f32_e32 v163, v161, v240
	v_fmac_f32_e32 v164, v161, v241
	v_fmac_f32_e32 v146, v160, v45
	v_fmac_f32_e32 v147, v157, v46
	v_fmac_f32_e32 v188, v148, v46
	v_fmac_f32_e32 v145, v157, v38
	v_fmac_f32_e32 v146, v148, v38
	v_fmac_f32_e32 v147, v68, v47
	v_fmac_f32_e32 v188, v162, v47
	v_fmac_f32_e32 v145, v68, v39
	v_fmac_f32_e32 v146, v162, v39
	v_fmac_f32_e32 v147, v69, v48
	v_fmac_f32_e32 v188, v163, v48
	v_fmac_f32_e32 v145, v69, v40
	v_fmac_f32_e32 v146, v163, v40
	v_fmac_f32_e32 v147, v158, v49
	v_fmac_f32_e32 v188, v164, v49
	v_fmac_f32_e32 v145, v158, v41
	v_add_f32_dpp v147, v147, v147 quad_perm:[1,0,3,2] row_mask:0xf bank_mask:0xf bound_ctrl:1
	v_add_f32_dpp v188, v188, v188 quad_perm:[1,0,3,2] row_mask:0xf bank_mask:0xf bound_ctrl:1
	s_nop 0
	v_add_f32_dpp v147, v147, v147 quad_perm:[2,3,0,1] row_mask:0xf bank_mask:0xf bound_ctrl:1
	v_add_f32_dpp v188, v188, v188 quad_perm:[2,3,0,1] row_mask:0xf bank_mask:0xf bound_ctrl:1
	v_fmac_f32_e32 v146, v164, v41
	v_add_f32_dpp v147, v147, v147 row_half_mirror row_mask:0xf bank_mask:0xf bound_ctrl:1
	v_add_f32_dpp v188, v188, v188 row_half_mirror row_mask:0xf bank_mask:0xf bound_ctrl:1
	s_waitcnt lgkmcnt(0)
	v_mul_f32_e32 v150, v52, v147
	v_fmac_f32_e32 v150, v155, v36
	ds_read_b128 v[46:49], v83 offset:23040
	ds_read_b128 v[42:45], v83 offset:23056
	v_mul_f32_e32 v151, v53, v147
	v_mul_f32_e32 v155, v33, v147
	v_fmac_f32_e32 v151, v156, v37
	v_mul_f32_e32 v70, v50, v147
	v_mul_f32_e32 v152, v30, v147
	v_fmac_f32_e32 v155, v158, v29
	v_mul_f32_e32 v156, v50, v188
	v_mul_f32_e32 v158, v52, v188
	v_fmac_f32_e32 v70, v153, v34
	v_mul_f32_e32 v149, v51, v147
	v_fmac_f32_e32 v152, v157, v26
	v_fmac_f32_e32 v156, v80, v34
	v_mul_f32_e32 v157, v51, v188
	v_fmac_f32_e32 v158, v159, v36
	v_mul_f32_e32 v159, v53, v188
	ds_read_b128 v[50:53], v83 offset:23296
	v_fmac_f32_e32 v159, v160, v37
	v_fmac_f32_e32 v70, v166, v54
	v_fmac_f32_e32 v149, v154, v35
	v_fmac_f32_e32 v156, v167, v54
	v_fmac_f32_e32 v157, v81, v35
	v_mul_f32_e32 v160, v30, v188
	v_mul_f32_e32 v153, v31, v147
	v_fmac_f32_e32 v149, v166, v55
	v_mul_f32_e32 v154, v32, v147
	v_mul_f32_e32 v147, v202, v70
	v_fmac_f32_e32 v157, v167, v55
	v_fmac_f32_e32 v160, v148, v26
	v_mul_f32_e32 v148, v202, v156
	v_fmac_f32_e32 v150, v166, v56
	v_fmac_f32_e32 v147, v149, v203
	v_fmac_f32_e32 v158, v167, v56
	v_fmac_f32_e32 v148, v157, v203
	v_fmac_f32_e32 v151, v166, v57
	v_fmac_f32_e32 v147, v150, v204
	v_fmac_f32_e32 v159, v167, v57
	v_mul_f32_e32 v161, v31, v188
	v_fmac_f32_e32 v148, v158, v204
	v_fmac_f32_e32 v153, v68, v27
	v_fmac_f32_e32 v152, v166, v194
	v_fmac_f32_e32 v147, v151, v205
	v_fmac_f32_e32 v160, v167, v194
	v_fmac_f32_e32 v161, v162, v27
	v_mul_f32_e32 v162, v32, v188
	v_fmac_f32_e32 v148, v159, v205
	v_fmac_f32_e32 v154, v69, v28
	v_fmac_f32_e32 v153, v166, v195
	v_fmac_f32_e32 v147, v152, v224
	v_fmac_f32_e32 v161, v167, v195
	v_fmac_f32_e32 v162, v163, v28
	v_mul_f32_e32 v163, v33, v188
	ds_read_b128 v[30:33], v83 offset:23312
	ds_read_b128 v[38:41], v83 offset:23552
	ds_read_b128 v[34:37], v83 offset:23568
	ds_read_b128 v[178:181], v83 offset:23808
	ds_read_b128 v[54:57], v83 offset:23824
	ds_read_b128 v[62:65], v83 offset:24064
	ds_read_b128 v[58:61], v83 offset:24080
	v_fmac_f32_e32 v148, v160, v224
	v_fmac_f32_e32 v163, v164, v29
	v_fmac_f32_e32 v154, v166, v196
	v_fmac_f32_e32 v147, v153, v225
	v_fmac_f32_e32 v162, v167, v196
	v_fmac_f32_e32 v148, v161, v225
	v_lshl_add_u64 v[80:81], v[66:67], 0, s[8:9]
	v_fmac_f32_e32 v155, v166, v197
	v_fmac_f32_e32 v147, v154, v226
	v_fmac_f32_e32 v163, v167, v197
	v_fmac_f32_e32 v148, v162, v226
	global_load_dwordx4 v[26:29], v[80:81], off
	v_fmac_f32_e32 v147, v155, v227
	s_waitcnt lgkmcnt(8)
	v_mul_f32_e32 v164, v70, v46
	v_mul_f32_e32 v165, v156, v46
	v_fmac_f32_e32 v164, v149, v47
	v_fmac_f32_e32 v165, v157, v47
	v_fmac_f32_e32 v164, v150, v48
	v_fmac_f32_e32 v165, v158, v48
	v_fmac_f32_e32 v164, v151, v49
	v_fmac_f32_e32 v165, v159, v49
	v_fmac_f32_e32 v164, v152, v42
	v_fmac_f32_e32 v165, v160, v42
	v_fmac_f32_e32 v164, v153, v43
	v_fmac_f32_e32 v165, v161, v43
	v_fmac_f32_e32 v164, v154, v44
	v_fmac_f32_e32 v165, v162, v44
	v_fmac_f32_e32 v164, v155, v45
	v_fmac_f32_e32 v165, v163, v45
	s_nop 0
	v_add_f32_dpp v164, v164, v164 quad_perm:[1,0,3,2] row_mask:0xf bank_mask:0xf bound_ctrl:1
	v_add_f32_dpp v165, v165, v165 quad_perm:[1,0,3,2] row_mask:0xf bank_mask:0xf bound_ctrl:1
	s_nop 0
	v_add_f32_dpp v164, v164, v164 quad_perm:[2,3,0,1] row_mask:0xf bank_mask:0xf bound_ctrl:1
	v_add_f32_dpp v165, v165, v165 quad_perm:[2,3,0,1] row_mask:0xf bank_mask:0xf bound_ctrl:1
	v_fmac_f32_e32 v148, v163, v227
	v_add_f32_dpp v164, v164, v164 row_half_mirror row_mask:0xf bank_mask:0xf bound_ctrl:1
	v_add_f32_dpp v165, v165, v165 row_half_mirror row_mask:0xf bank_mask:0xf bound_ctrl:1
	s_waitcnt lgkmcnt(4)
	v_mul_f32_e32 v42, v34, v164
	v_mul_f32_e32 v43, v35, v164
	v_mul_f32_e32 v34, v34, v165
	v_mul_f32_e32 v35, v35, v165
	v_fmac_f32_e32 v42, v152, v30
	v_fmac_f32_e32 v43, v153, v31
	v_mul_f32_e32 v44, v36, v164
	v_mul_f32_e32 v45, v37, v164
	v_fmac_f32_e32 v34, v160, v30
	v_fmac_f32_e32 v35, v161, v31
	v_mul_f32_e32 v36, v36, v165
	v_mul_f32_e32 v37, v37, v165
	v_lshl_add_u64 v[30:31], v[80:81], 0, s[8:9]
	v_fmac_f32_e32 v44, v154, v32
	v_fmac_f32_e32 v45, v155, v33
	v_fmac_f32_e32 v36, v162, v32
	v_fmac_f32_e32 v37, v163, v33
	global_load_dwordx4 v[30:33], v[30:31], off
	ds_read_b64 v[82:83], v82 offset:24320
	v_mul_f32_e32 v46, v38, v164
	v_mul_f32_e32 v38, v38, v165
	v_fmac_f32_e32 v46, v70, v50
	v_mul_f32_e32 v47, v39, v164
	v_mul_f32_e32 v48, v40, v164
	v_mul_f32_e32 v49, v41, v164
	v_fmac_f32_e32 v38, v156, v50
	v_mul_f32_e32 v39, v39, v165
	v_fmac_f32_e32 v47, v149, v51
	s_waitcnt lgkmcnt(0)
	v_fmac_f32_e32 v46, v82, v178
	v_fmac_f32_e32 v48, v150, v52
	v_fmac_f32_e32 v49, v151, v53
	v_fmac_f32_e32 v38, v83, v178
	v_fmac_f32_e32 v39, v157, v51
	v_mul_f32_e32 v40, v40, v165
	v_fmac_f32_e32 v47, v82, v179
	v_fmac_f32_e32 v48, v82, v180
	v_fmac_f32_e32 v49, v82, v181
	v_fmac_f32_e32 v42, v82, v54
	v_fmac_f32_e32 v43, v82, v55
	v_fmac_f32_e32 v44, v82, v56
	v_fmac_f32_e32 v45, v82, v57
	v_mul_f32_e32 v82, v62, v46
	v_fmac_f32_e32 v39, v83, v179
	v_fmac_f32_e32 v40, v158, v52
	v_mul_f32_e32 v41, v41, v165
	v_mul_f32_e32 v50, v62, v38
	v_fmac_f32_e32 v40, v83, v180
	v_fmac_f32_e32 v82, v47, v63
	v_fmac_f32_e32 v41, v159, v53
	v_fmac_f32_e32 v50, v39, v63
	v_fmac_f32_e32 v41, v83, v181
	v_fmac_f32_e32 v82, v48, v64
	v_fmac_f32_e32 v50, v40, v64
	v_fmac_f32_e32 v34, v83, v54
	v_fmac_f32_e32 v82, v49, v65
	v_fmac_f32_e32 v50, v41, v65
	v_fmac_f32_e32 v35, v83, v55
	v_fmac_f32_e32 v82, v42, v58
	v_fmac_f32_e32 v50, v34, v58
	v_fmac_f32_e32 v36, v83, v56
	v_fmac_f32_e32 v82, v43, v59
	v_fmac_f32_e32 v50, v35, v59
	v_fmac_f32_e32 v37, v83, v57
	v_fmac_f32_e32 v82, v44, v60
	v_fmac_f32_e32 v50, v36, v60
	v_readlane_b32 s70, v237, 8
	v_fmac_f32_e32 v82, v45, v61
	v_fmac_f32_e32 v50, v37, v61
	v_readlane_b32 s71, v237, 9
	v_readlane_b32 s72, v237, 10
	v_readlane_b32 s73, v237, 11
	v_readlane_b32 s74, v237, 12
	v_readlane_b32 s75, v237, 13
	v_readlane_b32 s76, v237, 14
	v_readlane_b32 s77, v237, 15
	v_readlane_b32 s78, v237, 16
	v_readlane_b32 s79, v237, 17
	v_add_f32_dpp v135, v135, v135 quad_perm:[1,0,3,2] row_mask:0xf bank_mask:0xf bound_ctrl:1
	v_add_f32_dpp v136, v136, v136 quad_perm:[1,0,3,2] row_mask:0xf bank_mask:0xf bound_ctrl:1
	v_add_f32_dpp v137, v137, v137 quad_perm:[1,0,3,2] row_mask:0xf bank_mask:0xf bound_ctrl:1
	v_add_f32_dpp v138, v138, v138 quad_perm:[1,0,3,2] row_mask:0xf bank_mask:0xf bound_ctrl:1
	v_add_f32_dpp v139, v139, v139 quad_perm:[1,0,3,2] row_mask:0xf bank_mask:0xf bound_ctrl:1
	v_add_f32_dpp v140, v140, v140 quad_perm:[1,0,3,2] row_mask:0xf bank_mask:0xf bound_ctrl:1
	v_add_f32_dpp v141, v141, v141 quad_perm:[1,0,3,2] row_mask:0xf bank_mask:0xf bound_ctrl:1
	v_add_f32_dpp v142, v142, v142 quad_perm:[1,0,3,2] row_mask:0xf bank_mask:0xf bound_ctrl:1
	v_add_f32_dpp v143, v143, v143 quad_perm:[1,0,3,2] row_mask:0xf bank_mask:0xf bound_ctrl:1
	v_add_f32_dpp v144, v144, v144 quad_perm:[1,0,3,2] row_mask:0xf bank_mask:0xf bound_ctrl:1
	v_add_f32_dpp v145, v145, v145 quad_perm:[1,0,3,2] row_mask:0xf bank_mask:0xf bound_ctrl:1
	v_add_f32_dpp v146, v146, v146 quad_perm:[1,0,3,2] row_mask:0xf bank_mask:0xf bound_ctrl:1
	v_add_f32_dpp v147, v147, v147 quad_perm:[1,0,3,2] row_mask:0xf bank_mask:0xf bound_ctrl:1
	v_add_f32_dpp v148, v148, v148 quad_perm:[1,0,3,2] row_mask:0xf bank_mask:0xf bound_ctrl:1
	v_add_f32_dpp v82, v82, v82 quad_perm:[1,0,3,2] row_mask:0xf bank_mask:0xf bound_ctrl:1
	v_add_f32_dpp v50, v50, v50 quad_perm:[1,0,3,2] row_mask:0xf bank_mask:0xf bound_ctrl:1
	v_add_f32_dpp v135, v135, v135 quad_perm:[2,3,0,1] row_mask:0xf bank_mask:0xf bound_ctrl:1
	v_add_f32_dpp v136, v136, v136 quad_perm:[2,3,0,1] row_mask:0xf bank_mask:0xf bound_ctrl:1
	v_add_f32_dpp v137, v137, v137 quad_perm:[2,3,0,1] row_mask:0xf bank_mask:0xf bound_ctrl:1
	v_add_f32_dpp v138, v138, v138 quad_perm:[2,3,0,1] row_mask:0xf bank_mask:0xf bound_ctrl:1
	v_add_f32_dpp v139, v139, v139 quad_perm:[2,3,0,1] row_mask:0xf bank_mask:0xf bound_ctrl:1
	v_add_f32_dpp v140, v140, v140 quad_perm:[2,3,0,1] row_mask:0xf bank_mask:0xf bound_ctrl:1
	v_add_f32_dpp v141, v141, v141 quad_perm:[2,3,0,1] row_mask:0xf bank_mask:0xf bound_ctrl:1
	v_add_f32_dpp v142, v142, v142 quad_perm:[2,3,0,1] row_mask:0xf bank_mask:0xf bound_ctrl:1
	v_add_f32_dpp v143, v143, v143 quad_perm:[2,3,0,1] row_mask:0xf bank_mask:0xf bound_ctrl:1
	v_add_f32_dpp v144, v144, v144 quad_perm:[2,3,0,1] row_mask:0xf bank_mask:0xf bound_ctrl:1
	v_add_f32_dpp v145, v145, v145 quad_perm:[2,3,0,1] row_mask:0xf bank_mask:0xf bound_ctrl:1
	v_add_f32_dpp v146, v146, v146 quad_perm:[2,3,0,1] row_mask:0xf bank_mask:0xf bound_ctrl:1
	v_add_f32_dpp v147, v147, v147 quad_perm:[2,3,0,1] row_mask:0xf bank_mask:0xf bound_ctrl:1
	v_add_f32_dpp v148, v148, v148 quad_perm:[2,3,0,1] row_mask:0xf bank_mask:0xf bound_ctrl:1
	v_add_f32_dpp v82, v82, v82 quad_perm:[2,3,0,1] row_mask:0xf bank_mask:0xf bound_ctrl:1
	v_add_f32_dpp v50, v50, v50 quad_perm:[2,3,0,1] row_mask:0xf bank_mask:0xf bound_ctrl:1
	v_add_f32_dpp v135, v135, v135 row_half_mirror row_mask:0xf bank_mask:0xf bound_ctrl:1
	v_add_f32_dpp v136, v136, v136 row_half_mirror row_mask:0xf bank_mask:0xf bound_ctrl:1
	v_add_f32_dpp v137, v137, v137 row_half_mirror row_mask:0xf bank_mask:0xf bound_ctrl:1
	v_add_f32_dpp v138, v138, v138 row_half_mirror row_mask:0xf bank_mask:0xf bound_ctrl:1
	v_add_f32_dpp v139, v139, v139 row_half_mirror row_mask:0xf bank_mask:0xf bound_ctrl:1
	v_add_f32_dpp v140, v140, v140 row_half_mirror row_mask:0xf bank_mask:0xf bound_ctrl:1
	v_add_f32_dpp v141, v141, v141 row_half_mirror row_mask:0xf bank_mask:0xf bound_ctrl:1
	v_add_f32_dpp v142, v142, v142 row_half_mirror row_mask:0xf bank_mask:0xf bound_ctrl:1
	v_add_f32_dpp v143, v143, v143 row_half_mirror row_mask:0xf bank_mask:0xf bound_ctrl:1
	v_add_f32_dpp v144, v144, v144 row_half_mirror row_mask:0xf bank_mask:0xf bound_ctrl:1
	v_add_f32_dpp v145, v145, v145 row_half_mirror row_mask:0xf bank_mask:0xf bound_ctrl:1
	v_add_f32_dpp v146, v146, v146 row_half_mirror row_mask:0xf bank_mask:0xf bound_ctrl:1
	v_add_f32_dpp v147, v147, v147 row_half_mirror row_mask:0xf bank_mask:0xf bound_ctrl:1
	v_add_f32_dpp v148, v148, v148 row_half_mirror row_mask:0xf bank_mask:0xf bound_ctrl:1
	v_add_f32_dpp v82, v82, v82 row_half_mirror row_mask:0xf bank_mask:0xf bound_ctrl:1
	v_add_f32_dpp v50, v50, v50 row_half_mirror row_mask:0xf bank_mask:0xf bound_ctrl:1
	v_cvt_pk_f16_f32 v54, v95, v96
	v_cvt_pk_f16_f32 v55, v98, v99
	v_cvt_pk_f16_f32 v56, v103, v121
	v_cvt_pk_f16_f32 v57, v125, v126
	v_cvt_pk_f16_f32 v58, v127, v128
	v_cvt_pk_f16_f32 v59, v129, v130
	v_cvt_pk_f16_f32 v60, v131, v132
	v_cvt_pk_f16_f32 v61, v133, v134
	v_cvt_pk_f16_f32 v69, v135, v136
	v_cvt_pk_f16_f32 v68, v137, v138
	v_cvt_pk_f16_f32 v67, v139, v140
	v_cvt_pk_f16_f32 v66, v141, v142
	v_cvt_pk_f16_f32 v65, v143, v144
	v_cvt_pk_f16_f32 v64, v145, v146
	v_cvt_pk_f16_f32 v63, v147, v148
	v_cvt_pk_f16_f32 v62, v82, v50
	v_and_b32_e32 v50, 1, v168
	v_and_b32_e32 v51, 7, v168
	v_cmp_ne_u32_e32 vcc, 0, v50
	s_and_b64 s[10:11], s[80:81], exec
	s_cselect_b32 s12, s84, 0x400
	s_lshl_b32 s13, s46, 4
	v_lshlrev_b32_e32 v51, 1, v51
	v_and_b32_e32 v50, 2, v168
	v_cndmask_b32_e32 v54, v54, v56, vcc
	v_cndmask_b32_e32 v55, v55, v57, vcc
	v_cndmask_b32_e32 v58, v58, v60, vcc
	v_cndmask_b32_e32 v59, v59, v61, vcc
	v_cndmask_b32_e32 v69, v69, v67, vcc
	v_cndmask_b32_e32 v68, v68, v66, vcc
	v_cndmask_b32_e32 v65, v65, v63, vcc
	v_cndmask_b32_e32 v64, v64, v62, vcc
	v_cmp_ne_u32_e32 vcc, 0, v50
	s_sub_i32 s15, s12, s13
	s_add_i32 s15, s15, -16
	s_cmp_eq_u32 s90, 0
	s_cselect_b32 s15, s13, s15
	s_cselect_b32 s14, 0, 15
	v_and_b32_e32 v50, 4, v168
	v_xor_b32_e32 v52, s14, v51
	v_cndmask_b32_e32 v54, v54, v58, vcc
	v_cndmask_b32_e32 v55, v55, v59, vcc
	v_cndmask_b32_e32 v69, v69, v65, vcc
	v_cndmask_b32_e32 v68, v68, v64, vcc
	v_cmp_ne_u32_e32 vcc, 0, v50
	s_ashr_i32 s12, s92, 6
	s_lshl_b32 s13, s12, 10
	s_add_i32 s68, s13, 0x2000
	s_lshl_b32 s69, s12, 8
	s_and_b64 s[12:13], s[80:81], exec
	s_cselect_b32 s68, s69, s68
	s_add_i32 s15, s68, s15
	v_lshlrev_b32_e32 v52, 12, v52
	v_lshl_add_u32 v52, v72, 1, v52
	v_cndmask_b32_e32 v54, v54, v69, vcc
	v_cndmask_b32_e32 v55, v55, v68, vcc
	s_mul_i32 s16, s90, 0x3000000
	s_lshl_b32 s17, s93, 7
	s_add_i32 s16, s16, s17
	s_lshl_b32 s17, s4, 1
	s_add_i32 s16, s16, s17
	s_lshl_b32 s17, s15, 12
	s_add_i32 s16, s16, s17
	s_add_u32 s10, s5, s16
	s_addc_u32 s11, s42, 0
	v_xor_b32_e32 v53, 0x1000, v52
	s_mov_b64 s[8:9], exec
	global_store_dword v52, v54, s[10:11]
	global_store_dword v53, v55, s[10:11]
